# code prefetch into L2 at grid barriers (waves 1-7 touch next 56KB of instructions) on top of small-loop load hoisting
# speedup vs baseline: 1.0075x; 1.0042x over previous
; __device__ __forceinline__ unsigned xb_ld(unsigned* p)              { return __hip_atomic_load(p, __ATOMIC_RELAXED, __HIP_MEMORY_SCOPE_AGENT); }
; __device__ __forceinline__ unsigned xb_add(unsigned* p, unsigned v) { return __hip_atomic_fetch_add(p, v, __ATOMIC_RELAXED, __HIP_MEMORY_SCOPE_AGENT); }
; __device__ __forceinline__ void xcd_barrier_complete(unsigned* bar, unsigned x, unsigned& nloc, unsigned& nx) {
;     const unsigned G = gridDim.x * gridDim.y * gridDim.z;
;     unsigned sum, cnt, mine, sp = 0u;
;     for (;;) {
;         sum = 0u; cnt = 0u; mine = 0u;
; #pragma unroll
;         for (unsigned j = 0; j < 16; ++j) { const unsigned c = xb_ld(&bar[XB_XCNT(j)]); sum += c; cnt += (c > 0u) ? 1u : 0u; mine = (j == x) ? c : mine; }
;         if (sum == G) break;
; __device__ __forceinline__ void xcd_barrier(const XcdBarrier& b) {
;     asm volatile("s_waitcnt vmcnt(0)" ::: "memory");
;     __syncthreads();
;     if (threadIdx.x == 0) {
;         unsigned* bar = b.bar;
;         __builtin_amdgcn_s_waitcnt(0);
;         unsigned nloc = b.st[0], nx = b.st[1];
;         if (nloc == 0u) { xcd_barrier_complete(bar, b.x, nloc, nx); b.st[0] = nloc; b.st[1] = nx; }
;         const unsigned old = xb_add(&bar[XB_XSUB(b.x)], 1u);
;         const unsigned gen = old / nloc;
;         if (old + 1u == (gen + 1u) * nloc) {
.LBB0_199:
	s_waitcnt vmcnt(0)
	s_barrier
	s_mov_b64 s[0:1], exec
	v_readlane_b32 s4, v254, 1
	v_readlane_b32 s5, v254, 2
	s_and_b64 s[4:5], s[0:1], s[4:5]
	s_mov_b64 exec, s[4:5]
	s_cbranch_execnz .Lpf_skip_1
	s_mov_b64 exec, s[0:1]
	s_getpc_b64 s[100:101]
	v_lshlrev_b32_e32 v251, 7, v178
	v_add_u32_e32 v251, 0xffffe000, v251
	global_load_dword v251, v251, s[100:101]
	s_mov_b64 exec, 0
.Lpf_skip_1:
	s_cbranch_execz .LBB0_251
	s_add_i32 s4, 0, 0x20000
	v_mov_b32_e32 v0, s4
	s_waitcnt vmcnt(0) expcnt(0) lgkmcnt(0)
	ds_read_b32 v2, v0
	s_add_i32 s4, 0, 0x20004
	v_mov_b32_e32 v0, s4
	ds_read_b32 v0, v0
	s_waitcnt lgkmcnt(1)
	v_cmp_ne_u32_e32 vcc, 0, v2
	s_cbranch_vccnz .LBB0_215
	s_add_u32 s4, s92, 0x1e8b7e00
	s_addc_u32 s5, s93, 0
	s_add_u32 s6, s92, 0x1e8b8000
	s_addc_u32 s7, s93, 0
	s_add_u32 s10, s92, 0x1e8b8100
	s_addc_u32 s11, s93, 0
	s_add_u32 s12, s92, 0x1e8b8200
	s_addc_u32 s13, s93, 0
	s_add_u32 s22, s92, 0x1e8b8300
	s_addc_u32 s23, s93, 0
	s_add_u32 s34, s92, 0x1e8b8400
	s_addc_u32 s35, s93, 0
	s_add_u32 s36, s92, 0x1e8b8500
	s_addc_u32 s37, s93, 0
	s_add_u32 s38, s92, 0x1e8b8600
	s_addc_u32 s39, s93, 0
	s_add_u32 s40, s92, 0x1e8b8700
	s_addc_u32 s41, s93, 0
	s_add_u32 s44, s92, 0x1e8b8800
	s_addc_u32 s45, s93, 0
	s_add_u32 s46, s92, 0x1e8b8900
	s_addc_u32 s47, s93, 0
	s_add_u32 s52, s92, 0x1e8b8a00
	s_addc_u32 s53, s93, 0
	s_add_u32 s54, s92, 0x1e8b8b00
	s_addc_u32 s55, s93, 0
	s_add_u32 s56, s92, 0x1e8b8c00
	s_addc_u32 s57, s93, 0
	s_add_u32 s58, s92, 0x1e8b8d00
	s_addc_u32 s59, s93, 0
	s_add_u32 s60, s92, 0x1e8b8e00
	v_readlane_b32 s3, v254, 0
	s_addc_u32 s61, s93, 0
	s_mul_i32 s16, s95, s3
	s_add_u32 s68, s92, 0x1e8b8f00
	s_mul_i32 s16, s16, s94
	s_addc_u32 s69, s93, 0
	s_mov_b32 s17, 1
	v_mov_b32_e32 v16, 0
	s_branch .LBB0_203

; __device__ __forceinline__ void small_swiglu(LAS unsigned char* lds, const bf16_t* A, const bf16_t* Bt, bf16_t* ACT, const float* ssq, const float* biasw, int G, int c) {
;     for (int un = c; un < DFF / 16; un += G) {
;         const int j0 = 16 * un, rg = (j0 >> 7) * 256 + (j0 & 127);
;         f32x4 o[2]; small_core<2>(lds, A, 1024, Bt + (size_t)rg * 1024, Bt + (size_t)(rg + 128) * 1024, 1024, o);
;         const int row = threadIdx.x >> 2, c4 = (threadIdx.x & 3) * 4, b = 16 + (row >> 4);
;         const float rstd = __builtin_amdgcn_rsqf(ssq[NP + row] * (1.0f / 1024.0f) + EPS);
;         const f32x4 g = o[0] * rstd + *(const f32x4*)(biasw + (size_t)b * 5632 + rg + c4), uu = o[1] * rstd + *(const f32x4*)(biasw + (size_t)b * 5632 + rg + 128 + c4);
; __device__ __forceinline__ void xcd_barrier(const XcdBarrier& b) {
;     ...
;     }
;     __syncthreads();
.LBB0_251:
	s_or_b64 exec, exec, s[0:1]
	s_add_u32 s44, s92, 0x93c0000
	s_addc_u32 s45, s93, 0
	s_add_u32 s48, s92, 0x9340000
	s_addc_u32 s49, s93, 0
	s_cmpk_lt_i32 s2, 0xb0
	s_cselect_b64 s[0:1], -1, 0
	v_writelane_b32 v254, s0, 56
	s_cmpk_gt_i32 s2, 0xaf
	v_lshrrev_b32_e32 v253, 2, v178
	v_writelane_b32 v254, s1, 57
	s_waitcnt lgkmcnt(0)
	s_barrier
	s_waitcnt vmcnt(0)
	s_cbranch_scc1 .LBB0_259
	v_or_b32_e32 v7, 0x8000, v253
	v_lshlrev_b32_e32 v0, 2, v7
	v_mov_b32_e32 v1, 0
	v_lshl_add_u64 v[68:69], s[8:9], 0, v[0:1]
	v_mul_u32_u24_e32 v0, 0x1600, v179
	v_and_b32_e32 v6, 12, v239
	s_movk_i32 s0, 0x1600
	v_lshlrev_b32_e32 v0, 2, v0
	v_mov_b64_e32 v[4:5], s[44:45]
	v_lshl_add_u64 v[2:3], s[50:51], 0, v[0:1]
	v_mad_u64_u32 v[4:5], s[0:1], v7, s0, v[4:5]
	v_lshlrev_b32_e32 v0, 1, v6
	v_lshl_add_u64 v[70:71], v[4:5], 0, v[0:1]
	v_lshlrev_b32_e32 v0, 2, v6
	v_lshl_add_u64 v[2:3], v[2:3], 0, v[0:1]
	s_mov_b64 s[0:1], 0x58000
	v_lshl_add_u64 v[72:73], v[2:3], 0, s[0:1]
	s_mov_b32 s1, 0
	s_mov_b64 s[4:5], 0x8000
	s_mov_b64 s[6:7], 0x10000
	s_mov_b64 s[10:11], 0x18000
	s_mov_b64 s[12:13], 0x20000
	s_mov_b64 s[22:23], 0x28000
	s_mov_b64 s[34:35], 0x30000
	s_mov_b64 s[36:37], 0x38000
	v_mov_b32_e32 v94, 0x3727c5ac
	s_mov_b32 s16, s2
	s_branch .LBB0_254

; __device__ __forceinline__ unsigned xb_ld(unsigned* p)              { return __hip_atomic_load(p, __ATOMIC_RELAXED, __HIP_MEMORY_SCOPE_AGENT); }
; __device__ __forceinline__ unsigned xb_add(unsigned* p, unsigned v) { return __hip_atomic_fetch_add(p, v, __ATOMIC_RELAXED, __HIP_MEMORY_SCOPE_AGENT); }
; __device__ __forceinline__ void xcd_barrier_complete(unsigned* bar, unsigned x, unsigned& nloc, unsigned& nx) {
;     const unsigned G = gridDim.x * gridDim.y * gridDim.z;
;     unsigned sum, cnt, mine, sp = 0u;
;     for (;;) {
;         sum = 0u; cnt = 0u; mine = 0u;
; #pragma unroll
;         for (unsigned j = 0; j < 16; ++j) { const unsigned c = xb_ld(&bar[XB_XCNT(j)]); sum += c; cnt += (c > 0u) ? 1u : 0u; mine = (j == x) ? c : mine; }
;         if (sum == G) break;
; __device__ __forceinline__ void xcd_barrier(const XcdBarrier& b) {
;     ...
;     if (threadIdx.x == 0) {
;         unsigned* bar = b.bar;
;         __builtin_amdgcn_s_waitcnt(0);
;         unsigned nloc = b.st[0], nx = b.st[1];
;         if (nloc == 0u) { xcd_barrier_complete(bar, b.x, nloc, nx); b.st[0] = nloc; b.st[1] = nx; }
;         const unsigned old = xb_add(&bar[XB_XSUB(b.x)], 1u);
;         const unsigned gen = old / nloc;
;         if (old + 1u == (gen + 1u) * nloc) {
.Lpf_skip_2:
	s_cbranch_execz .LBB0_327
	s_add_i32 s4, 0, 0x20000
	v_mov_b32_e32 v0, s4
	s_waitcnt vmcnt(0) expcnt(0) lgkmcnt(0)
	ds_read_b32 v2, v0
	s_add_i32 s4, 0, 0x20004
	v_mov_b32_e32 v0, s4
	ds_read_b32 v0, v0
	s_waitcnt lgkmcnt(1)
	v_cmp_ne_u32_e32 vcc, 0, v2
	s_cbranch_vccnz .LBB0_291
	s_add_u32 s4, s92, 0x1e8b7e00
	s_addc_u32 s5, s93, 0
	s_add_u32 s6, s92, 0x1e8b8000
	s_addc_u32 s7, s93, 0
	s_add_u32 s8, s92, 0x1e8b8100
	s_addc_u32 s9, s93, 0
	s_add_u32 s10, s92, 0x1e8b8200
	s_addc_u32 s11, s93, 0
	s_add_u32 s12, s92, 0x1e8b8300
	s_addc_u32 s13, s93, 0
	s_add_u32 s22, s92, 0x1e8b8400
	s_addc_u32 s23, s93, 0
	s_add_u32 s34, s92, 0x1e8b8500
	s_addc_u32 s35, s93, 0
	s_add_u32 s36, s92, 0x1e8b8600
	s_addc_u32 s37, s93, 0
	s_add_u32 s38, s92, 0x1e8b8700
	s_addc_u32 s39, s93, 0
	s_add_u32 s40, s92, 0x1e8b8800
	s_addc_u32 s41, s93, 0
	s_add_u32 s52, s92, 0x1e8b8900
	s_addc_u32 s53, s93, 0
	s_add_u32 s54, s92, 0x1e8b8a00
	s_addc_u32 s55, s93, 0
	s_add_u32 s56, s92, 0x1e8b8b00
	s_addc_u32 s57, s93, 0
	s_add_u32 s58, s92, 0x1e8b8c00
	s_addc_u32 s59, s93, 0
	s_add_u32 s60, s92, 0x1e8b8d00
	s_addc_u32 s61, s93, 0
	s_add_u32 s68, s92, 0x1e8b8e00
	v_readlane_b32 s3, v254, 0
	s_addc_u32 s69, s93, 0
	s_mul_i32 s16, s95, s3
	s_add_u32 s70, s92, 0x1e8b8f00
	s_mul_i32 s16, s16, s94
	s_addc_u32 s71, s93, 0
	s_mov_b32 s17, 1
	v_mov_b32_e32 v16, 0
	s_branch .LBB0_279

; __device__ __forceinline__ void small_resid(LAS unsigned char* lds, const bf16_t* A, int K, const bf16_t* Bt, const float* xs_in, float* X, const float* modp, float coef, ...
;     for (int un = c; un < 64; un += G) {
;         f32x4 o[1]; small_core<1>(lds, A, K, Bt + (size_t)(16 * un) * K, Bt, K, o);
;         const int row = threadIdx.x >> 2, col = 16 * un + (threadIdx.x & 3) * 4, b = 16 + (row >> 4);
; __device__ __forceinline__ void xcd_barrier(const XcdBarrier& b) {
;     ...
;     }
;     __syncthreads();
.LBB0_327:
	s_or_b64 exec, exec, s[0:1]
	s_add_u32 s34, s92, 0x1e827c00
	s_addc_u32 s35, s93, 0
	s_add_u32 s28, s92, 0x143c0000
	s_addc_u32 s29, s93, 0
	s_add_u32 s36, s92, 0x2000
	s_addc_u32 s37, s93, 0
	s_add_u32 s38, s92, 0x1e2a8000
	s_addc_u32 s39, s93, 0
	s_cmp_lt_i32 s2, 64
	s_cselect_b64 s[0:1], -1, 0
	v_writelane_b32 v254, s0, 60
	s_cmp_gt_i32 s2, 63
	s_waitcnt lgkmcnt(0)
	v_writelane_b32 v254, s1, 61
	s_barrier
	s_waitcnt vmcnt(0)
	s_cbranch_scc1 .LBB0_337
	v_lshlrev_b32_e32 v0, 9, v178
	v_and_b32_e32 v32, 0x7f800, v0
	v_mov_b32_e32 v33, 0
	v_or_b32_e32 v2, 16, v179
	v_lshl_add_u64 v[0:1], s[42:43], 0, v[32:33]
	s_mov_b64 s[0:1], 0x4000000
	v_lshl_add_u64 v[34:35], v[0:1], 0, s[0:1]
	v_lshlrev_b32_e32 v32, 12, v2
	s_mov_b32 s0, 0x9000
	v_mov_b64_e32 v[0:1], s[36:37]
	v_lshl_add_u64 v[36:37], s[34:35], 0, v[32:33]
	v_mad_u64_u32 v[38:39], s[0:1], v2, s0, v[0:1]
	v_lshl_add_u64 v[40:41], s[38:39], 0, v[32:33]
	v_and_b32_e32 v0, 3, v178
	v_and_b32_e32 v32, 0x3fc, v178
	v_cmp_eq_u32_e64 s[0:1], 0, v0
	v_lshl_add_u64 v[0:1], s[92:93], 0, v[32:33]
	s_mov_b64 s[6:7], 0x1e786400
	v_and_b32_e32 v64, 12, v239
	s_mov_b32 s5, 0
	v_lshl_add_u64 v[42:43], v[0:1], 0, s[6:7]
	s_mov_b64 s[6:7], 0x84000
	s_mov_b64 s[8:9], 0x9a000
	v_mbcnt_hi_u32_b32 v65, -1, v161
	s_mov_b32 s12, s2
	s_branch .LBB0_330

; __device__ __forceinline__ unsigned xb_ld(unsigned* p)              { return __hip_atomic_load(p, __ATOMIC_RELAXED, __HIP_MEMORY_SCOPE_AGENT); }
; __device__ __forceinline__ unsigned xb_add(unsigned* p, unsigned v) { return __hip_atomic_fetch_add(p, v, __ATOMIC_RELAXED, __HIP_MEMORY_SCOPE_AGENT); }
; __device__ __forceinline__ void xcd_barrier_complete(unsigned* bar, unsigned x, unsigned& nloc, unsigned& nx) {
;     const unsigned G = gridDim.x * gridDim.y * gridDim.z;
;     unsigned sum, cnt, mine, sp = 0u;
;     for (;;) {
;         sum = 0u; cnt = 0u; mine = 0u;
; #pragma unroll
;         for (unsigned j = 0; j < 16; ++j) { const unsigned c = xb_ld(&bar[XB_XCNT(j)]); sum += c; cnt += (c > 0u) ? 1u : 0u; mine = (j == x) ? c : mine; }
;         if (sum == G) break;
; __device__ __forceinline__ void xcd_barrier(const XcdBarrier& b) {
;     asm volatile("s_waitcnt vmcnt(0)" ::: "memory");
;     __syncthreads();
;     if (threadIdx.x == 0) {
;         unsigned* bar = b.bar;
;         __builtin_amdgcn_s_waitcnt(0);
;         unsigned nloc = b.st[0], nx = b.st[1];
;         if (nloc == 0u) { xcd_barrier_complete(bar, b.x, nloc, nx); b.st[0] = nloc; b.st[1] = nx; }
;         const unsigned old = xb_add(&bar[XB_XSUB(b.x)], 1u);
;         const unsigned gen = old / nloc;
;         if (old + 1u == (gen + 1u) * nloc) {
.LBB0_383:
	s_waitcnt vmcnt(0)
	s_waitcnt lgkmcnt(0)
	s_barrier
	s_mov_b64 s[0:1], exec
	v_readlane_b32 s4, v254, 1
	v_readlane_b32 s5, v254, 2
	s_and_b64 s[4:5], s[0:1], s[4:5]
	s_mov_b64 exec, s[4:5]
	s_cbranch_execnz .Lpf_skip_3
	s_mov_b64 exec, s[0:1]
	s_getpc_b64 s[100:101]
	v_lshlrev_b32_e32 v251, 7, v178
	v_add_u32_e32 v251, 0xffffe000, v251
	global_load_dword v251, v251, s[100:101]
	s_mov_b64 exec, 0
.Lpf_skip_3:
	s_cbranch_execz .LBB0_435
	s_add_i32 s4, 0, 0x20000
	v_mov_b32_e32 v0, s4
	s_waitcnt vmcnt(0) expcnt(0) lgkmcnt(0)
	ds_read_b32 v2, v0
	s_add_i32 s4, 0, 0x20004
	v_mov_b32_e32 v0, s4
	ds_read_b32 v0, v0
	s_waitcnt lgkmcnt(1)
	v_cmp_ne_u32_e32 vcc, 0, v2
	s_cbranch_vccnz .LBB0_399
	s_add_u32 s4, s92, 0x1e8b7e00
	s_addc_u32 s5, s93, 0
	s_add_u32 s6, s92, 0x1e8b8000
	s_addc_u32 s7, s93, 0
	s_add_u32 s8, s92, 0x1e8b8100
	s_addc_u32 s9, s93, 0
	s_add_u32 s10, s92, 0x1e8b8200
	s_addc_u32 s11, s93, 0
	s_add_u32 s12, s92, 0x1e8b8300
	s_addc_u32 s13, s93, 0
	s_add_u32 s34, s92, 0x1e8b8400
	s_addc_u32 s35, s93, 0
	s_add_u32 s36, s92, 0x1e8b8500
	s_addc_u32 s37, s93, 0
	s_add_u32 s38, s92, 0x1e8b8600
	s_addc_u32 s39, s93, 0
	s_add_u32 s40, s92, 0x1e8b8700
	s_addc_u32 s41, s93, 0
	s_add_u32 s52, s92, 0x1e8b8800
	s_addc_u32 s53, s93, 0
	s_add_u32 s54, s92, 0x1e8b8900
	s_addc_u32 s55, s93, 0
	s_add_u32 s56, s92, 0x1e8b8a00
	s_addc_u32 s57, s93, 0
	s_add_u32 s58, s92, 0x1e8b8b00
	s_addc_u32 s59, s93, 0
	s_add_u32 s60, s92, 0x1e8b8c00
	s_addc_u32 s61, s93, 0
	s_add_u32 s68, s92, 0x1e8b8d00
	s_addc_u32 s69, s93, 0
	s_add_u32 s70, s92, 0x1e8b8e00
	v_readlane_b32 s3, v254, 0
	s_addc_u32 s71, s93, 0
	s_mul_i32 s16, s95, s3
	s_add_u32 s72, s92, 0x1e8b8f00
	s_mul_i32 s16, s16, s94
	s_addc_u32 s73, s93, 0
	s_mov_b32 s17, 1
	v_mov_b32_e32 v16, 0
	s_branch .LBB0_387

; __device__ __forceinline__ void small_bf16(LAS unsigned char* lds, const bf16_t* A, int lda, int K, const bf16_t* Bt, int N, bf16_t* O, int ldc, float scale,
;                                            const float* ssq, const float* biasw, int ldb, int G, int c) {
;     for (int un = c; un < N / 16; un += G) {
;         f32x4 o[1]; small_core<1>(lds, A, lda, Bt + (size_t)(16 * un) * K, Bt, K, o);
;         const int row = threadIdx.x >> 2, col = 16 * un + (threadIdx.x & 3) * 4, b = 16 + (row >> 4);
; __device__ __forceinline__ void xcd_barrier(const XcdBarrier& b) {
;     ...
;     }
;     __syncthreads();
.LBB0_435:
	v_writelane_b32 v255, s84, 8
	s_nop 1
	v_writelane_b32 v255, s85, 9
	s_or_b64 exec, exec, s[0:1]
	s_abs_i32 s0, s94
	s_waitcnt lgkmcnt(0)
	v_cvt_f32_u32_e32 v0, s0
	s_sub_i32 s4, 0, s0
	s_add_i32 s1, s2, 0x80
	s_ashr_i32 s84, s1, 31
	v_rcp_iflag_f32_e32 v0, v0
	s_abs_i32 s1, s1
	s_barrier
	s_waitcnt vmcnt(0)
	v_mul_f32_e32 v0, 0x4f7ffffe, v0
	v_cvt_u32_f32_e32 v0, v0
	s_nop 0
	v_readfirstlane_b32 s5, v0
	s_mul_i32 s4, s4, s5
	s_mul_hi_u32 s4, s5, s4
	s_add_i32 s5, s5, s4
	s_mul_hi_u32 s4, s1, s5
	s_mul_i32 s4, s4, s0
	s_sub_i32 s1, s1, s4
	s_sub_i32 s4, s1, s0
	s_cmp_ge_u32 s1, s0
	s_cselect_b32 s1, s4, s1
	s_sub_i32 s4, s1, s0
	s_cmp_ge_u32 s1, s0
	s_cselect_b32 s0, s4, s1
	s_xor_b32 s85, s0, s84
	s_sub_i32 s67, s85, s84
	s_cmpk_gt_i32 s67, 0x8b
	s_mov_b32 s1, 0
	s_cbranch_scc1 .LBB0_443
	v_and_b32_e32 v32, 0x3fc, v178
	v_mov_b32_e32 v33, 0
	v_lshl_add_u64 v[0:1], s[22:23], 0, v[32:33]
	s_mov_b64 s[4:5], 0x20000
	v_lshl_add_u64 v[34:35], v[0:1], 0, s[4:5]
	v_mul_u32_u24_e32 v0, 0x900, v179
	v_lshlrev_b32_e32 v32, 2, v0
	v_lshl_add_u64 v[0:1], s[18:19], 0, v[32:33]
	s_mov_b64 s[6:7], 0x24000
	v_lshl_add_u64 v[36:37], v[0:1], 0, s[6:7]
	v_mul_u32_u24_e32 v0, 0x900, v253
	v_lshlrev_b32_e32 v32, 1, v0
	v_lshl_add_u64 v[0:1], s[44:45], 0, v[32:33]
	s_mov_b64 s[6:7], 0x9000000
	v_and_b32_e32 v60, 12, v239
	v_lshl_add_u64 v[38:39], v[0:1], 0, s[6:7]
	s_mov_b64 s[6:7], 0x30000
	s_mov_b64 s[8:9], 0x38000
	v_mov_b32_e32 v61, 0x3727c5ac
	s_mov_b32 s16, s67
	s_branch .LBB0_438

; __device__ __forceinline__ unsigned xb_ld(unsigned* p)              { return __hip_atomic_load(p, __ATOMIC_RELAXED, __HIP_MEMORY_SCOPE_AGENT); }
; __device__ __forceinline__ unsigned xb_add(unsigned* p, unsigned v) { return __hip_atomic_fetch_add(p, v, __ATOMIC_RELAXED, __HIP_MEMORY_SCOPE_AGENT); }
; __device__ __forceinline__ void xcd_barrier_complete(unsigned* bar, unsigned x, unsigned& nloc, unsigned& nx) {
;     const unsigned G = gridDim.x * gridDim.y * gridDim.z;
;     unsigned sum, cnt, mine, sp = 0u;
;     for (;;) {
;         sum = 0u; cnt = 0u; mine = 0u;
; #pragma unroll
;         for (unsigned j = 0; j < 16; ++j) { const unsigned c = xb_ld(&bar[XB_XCNT(j)]); sum += c; cnt += (c > 0u) ? 1u : 0u; mine = (j == x) ? c : mine; }
;         if (sum == G) break;
; __device__ __forceinline__ void xcd_barrier(const XcdBarrier& b) {
;     ...
;     if (threadIdx.x == 0) {
;         unsigned* bar = b.bar;
;         __builtin_amdgcn_s_waitcnt(0);
;         unsigned nloc = b.st[0], nx = b.st[1];
;         if (nloc == 0u) { xcd_barrier_complete(bar, b.x, nloc, nx); b.st[0] = nloc; b.st[1] = nx; }
;         const unsigned old = xb_add(&bar[XB_XSUB(b.x)], 1u);
;         const unsigned gen = old / nloc;
;         if (old + 1u == (gen + 1u) * nloc) {
.Lpf_skip_4:
	s_cbranch_execz .LBB0_511
	s_add_i32 s4, 0, 0x20000
	v_mov_b32_e32 v0, s4
	s_waitcnt vmcnt(0) expcnt(0) lgkmcnt(0)
	ds_read_b32 v2, v0
	s_add_i32 s4, 0, 0x20004
	v_mov_b32_e32 v0, s4
	ds_read_b32 v0, v0
	s_waitcnt lgkmcnt(1)
	v_cmp_ne_u32_e32 vcc, 0, v2
	s_cbranch_vccnz .LBB0_475
	s_add_u32 s4, s92, 0x1e8b7e00
	s_addc_u32 s5, s93, 0
	s_add_u32 s6, s92, 0x1e8b8000
	s_addc_u32 s7, s93, 0
	s_add_u32 s8, s92, 0x1e8b8100
	s_addc_u32 s9, s93, 0
	s_add_u32 s10, s92, 0x1e8b8200
	s_addc_u32 s11, s93, 0
	s_add_u32 s12, s92, 0x1e8b8300
	s_addc_u32 s13, s93, 0
	s_add_u32 s14, s92, 0x1e8b8400
	s_addc_u32 s15, s93, 0
	s_add_u32 s18, s92, 0x1e8b8500
	s_addc_u32 s19, s93, 0
	s_add_u32 s22, s92, 0x1e8b8600
	s_addc_u32 s23, s93, 0
	s_add_u32 s34, s92, 0x1e8b8700
	s_addc_u32 s35, s93, 0
	s_add_u32 s36, s92, 0x1e8b8800
	s_addc_u32 s37, s93, 0
	s_add_u32 s38, s92, 0x1e8b8900
	s_addc_u32 s39, s93, 0
	s_add_u32 s40, s92, 0x1e8b8a00
	s_addc_u32 s41, s93, 0
	s_add_u32 s52, s92, 0x1e8b8b00
	s_addc_u32 s53, s93, 0
	s_add_u32 s54, s92, 0x1e8b8c00
	s_addc_u32 s55, s93, 0
	s_add_u32 s56, s92, 0x1e8b8d00
	s_addc_u32 s57, s93, 0
	s_add_u32 s58, s92, 0x1e8b8e00
	v_readlane_b32 s3, v254, 0
	s_addc_u32 s59, s93, 0
	s_mul_i32 s16, s95, s3
	s_add_u32 s60, s92, 0x1e8b8f00
	s_mul_i32 s16, s16, s94
	s_addc_u32 s61, s93, 0
	s_mov_b32 s17, 1
	v_mov_b32_e32 v16, 0
	s_branch .LBB0_463

; __global__ void __launch_bounds__(512, 2) fwd_kernel(Params P) {
;     ...
;         const float* qng = P.in[18]; const float* kvg = P.in[20];
;         const int dsub = (lane & 3) * 8; const bool ishi = (lane & 4) != 0;
;         for (int row = gw; row < MR; row += NGW) {
;             bf16_t* pr = BIG + (size_t)row * PROJ_LD;
;             const int pos = row_pos(row);
;             float cs[8], sn[8];
; #pragma unroll
;             for (int i = 0; i < 8; ++i) { const float inv = __builtin_amdgcn_exp2f(-(float)(dsub + i) * (13.287712379549449f / 32.0f)); const float ang_ = (float)pos * inv; sn[i] = __sinf(ang_); cs[i] = __cosf(ang_); }
;             { const u32x4 raw = *(const u32x4*)(pr + lane * 8); float x[8], y[8];
.LBB0_511:
	s_or_b64 exec, exec, s[0:1]
	v_readlane_b32 s4, v254, 54
	v_readlane_b32 s5, v254, 55
	s_add_u32 s22, s92, 0x1a640000
	s_addc_u32 s23, s93, 0
	s_waitcnt lgkmcnt(0)
	v_cndmask_b32_e64 v0, 0, 1, s[4:5]
	v_cmp_ne_u32_e64 s[0:1], 1, v0
	s_add_u32 s86, s92, 0x1ba80000
	s_addc_u32 s87, s93, 0
	v_writelane_b32 v255, s0, 10
	s_andn2_b64 vcc, exec, s[4:5]
	v_and_b32_e32 v183, 24, v252
	v_writelane_b32 v255, s1, 11
	s_barrier
	s_waitcnt vmcnt(0)
	s_cbranch_vccnz .LBB0_536
	v_and_b32_e32 v0, 4, v178
	v_cmp_eq_u32_e64 s[0:1], 0, v0
	v_mbcnt_hi_u32_b32 v0, -1, v161
	v_and_b32_e32 v2, 64, v0
	v_xor_b32_e32 v1, 4, v0
	v_add_u32_e32 v2, 64, v2
	v_cmp_lt_i32_e32 vcc, v1, v2
	v_readlane_b32 s4, v255, 8
	v_readlane_b32 s12, v254, 3
	v_cndmask_b32_e32 v1, v0, v1, vcc
	v_lshlrev_b32_e32 v52, 2, v1
	v_xor_b32_e32 v1, 1, v0
	v_cmp_lt_i32_e32 vcc, v1, v2
	v_mov_b32_e32 v181, 0
	v_readlane_b32 s5, v255, 9
	v_cndmask_b32_e32 v1, v0, v1, vcc
	v_lshlrev_b32_e32 v53, 2, v1
	v_xor_b32_e32 v1, 2, v0
	v_cmp_lt_i32_e32 vcc, v1, v2
	s_ashr_i32 s97, s96, 31
	v_readlane_b32 s18, v254, 9
	v_cndmask_b32_e32 v1, v0, v1, vcc
	v_lshlrev_b32_e32 v54, 2, v1
	v_xor_b32_e32 v1, 8, v0
	v_cmp_lt_i32_e32 vcc, v1, v2
	v_readlane_b32 s19, v254, 10
	v_lshl_add_u64 v[8:9], s[4:5], 0, v[180:181]
	v_cndmask_b32_e32 v1, v0, v1, vcc
	v_lshlrev_b32_e32 v55, 2, v1
	v_xor_b32_e32 v1, 16, v0
	v_cmp_lt_i32_e32 vcc, v1, v2
	s_ashr_i32 s25, s24, 31
	s_lshl_b64 s[4:5], s[96:97], 8
	v_cndmask_b32_e32 v1, v0, v1, vcc
	v_lshlrev_b32_e32 v56, 2, v1
	v_xor_b32_e32 v1, 32, v0
	v_cmp_lt_i32_e32 vcc, v1, v2
	v_readlane_b32 s16, v254, 7
	s_mov_b64 s[58:59], s[18:19]
	v_cndmask_b32_e32 v0, v0, v1, vcc
	v_lshlrev_b32_e32 v57, 2, v0
	v_cvt_f32_ubyte0_e32 v0, v183
	v_mul_f32_e32 v0, 0xbed49a78, v0
	v_exp_f32_e32 v58, v0
	v_or_b32_e32 v0, 1, v183
	v_cvt_f32_ubyte0_e32 v0, v0
	v_mul_f32_e32 v0, 0xbed49a78, v0
	v_exp_f32_e32 v59, v0
	v_or_b32_e32 v0, 2, v183
	v_cvt_f32_ubyte0_e32 v0, v0
	v_mul_f32_e32 v0, 0xbed49a78, v0
	v_exp_f32_e32 v60, v0
	v_or_b32_e32 v0, 3, v183
	v_cvt_f32_ubyte0_e32 v0, v0
	v_mul_f32_e32 v0, 0xbed49a78, v0
	v_exp_f32_e32 v61, v0
	v_or_b32_e32 v0, 4, v183
	v_cvt_f32_ubyte0_e32 v0, v0
	v_mul_f32_e32 v0, 0xbed49a78, v0
	v_exp_f32_e32 v62, v0
	v_or_b32_e32 v0, 5, v183
	v_cvt_f32_ubyte0_e32 v0, v0
	v_mul_f32_e32 v0, 0xbed49a78, v0
	v_exp_f32_e32 v63, v0
	v_or_b32_e32 v0, 6, v183
	v_readlane_b32 s17, v254, 8
	s_add_u32 s16, s58, s4
	v_cvt_f32_ubyte0_e32 v0, v0
	s_addc_u32 s17, s59, s5
	s_lshl_b64 s[18:19], s[24:25], 8
	s_lshl_b64 s[4:5], s[96:97], 10
	v_mul_f32_e32 v0, 0xbed49a78, v0
	s_add_u32 s34, s58, s4
	v_exp_f32_e32 v64, v0
	v_or_b32_e32 v0, 7, v183
	s_addc_u32 s35, s59, s5
	s_lshl_b64 s[36:37], s[24:25], 10
	s_lshl_b64 s[38:39], s[96:97], 9
	s_lshl_b64 s[40:41], s[24:25], 9
	s_lshl_b64 s[4:5], s[96:97], 11
	v_cvt_f32_ubyte0_e32 v0, v0
	s_add_u32 s52, s58, s4
	v_mul_f32_e32 v0, 0xbed49a78, v0
	s_addc_u32 s53, s59, s5
	s_lshl_b64 s[54:55], s[24:25], 11
	s_mul_i32 s4, s96, 0x1200
	v_exp_f32_e32 v65, v0
	s_mul_hi_i32 s5, s96, 0x1200
	s_add_u32 s4, s92, s4
	v_readlane_b32 s68, v254, 14
	s_addc_u32 s5, s93, s5
	v_lshlrev_b32_e32 v12, 5, v238
	v_mov_b32_e32 v13, v181
	v_readlane_b32 s72, v254, 18
	v_readlane_b32 s73, v254, 19
	v_readlane_b32 s76, v254, 22
	v_readlane_b32 s77, v254, 23
	v_lshl_add_u64 v[0:1], s[4:5], 0, v[180:181]
	s_mov_b64 s[4:5], 0x93c0000
	v_lshl_add_u64 v[10:11], s[88:89], 0, v[180:181]
	v_cmp_gt_u32_e64 s[6:7], 48, v238
	v_lshl_add_u64 v[14:15], s[72:73], 0, v[12:13]
	v_cmp_gt_u32_e64 s[8:9], 32, v238
	v_lshl_add_u64 v[16:17], s[76:77], 0, v[12:13]
	v_lshl_add_u64 v[18:19], s[22:23], 0, v[180:181]
	v_cmp_gt_u32_e64 s[10:11], 8, v238
	v_lshl_add_u64 v[20:21], s[86:87], 0, v[180:181]
	v_lshl_add_u64 v[22:23], v[0:1], 0, s[4:5]
	s_mul_hi_i32 s57, s24, 0x1200
	s_mul_i32 s56, s24, 0x1200
	s_mov_b32 s58, 0x3e38aa3b
	v_mov_b32_e32 v66, 0x3727c5ac
	s_mov_b32 s59, 0xf800000
	v_mov_b32_e32 v67, 0x260
	s_mov_b64 s[60:61], s[96:97]
	v_readlane_b32 s69, v254, 15
	v_readlane_b32 s70, v254, 16
	v_readlane_b32 s71, v254, 17
	v_readlane_b32 s74, v254, 20
	v_readlane_b32 s75, v254, 21
	v_readlane_b32 s78, v254, 24
	v_readlane_b32 s79, v254, 25
	v_readlane_b32 s80, v254, 26
	v_readlane_b32 s81, v254, 27
	v_readlane_b32 s82, v254, 28
	v_readlane_b32 s83, v254, 29
	v_readlane_b32 s13, v254, 4
	v_readlane_b32 s14, v254, 5
	v_readlane_b32 s15, v254, 6
	s_branch .LBB0_515

; __device__ __forceinline__ unsigned xb_ld(unsigned* p)              { return __hip_atomic_load(p, __ATOMIC_RELAXED, __HIP_MEMORY_SCOPE_AGENT); }
; __device__ __forceinline__ void xcd_barrier_complete(unsigned* bar, unsigned x, unsigned& nloc, unsigned& nx) {
;     const unsigned G = gridDim.x * gridDim.y * gridDim.z;
;     unsigned sum, cnt, mine, sp = 0u;
;     for (;;) {
;         sum = 0u; cnt = 0u; mine = 0u;
; #pragma unroll
;         for (unsigned j = 0; j < 16; ++j) { const unsigned c = xb_ld(&bar[XB_XCNT(j)]); sum += c; cnt += (c > 0u) ? 1u : 0u; mine = (j == x) ? c : mine; }
;         if (sum == G) break;
;         __builtin_amdgcn_s_sleep(1);
;         if ((++sp & 255u) == 0u) { if (xb_ld(&bar[XB_TMO])) break; if (sp > XB_SPIN_CAP) { atomicAdd(&bar[XB_TMO], 1u); break; } }
;     }
;     nloc = mine > 0u ? mine : 1u; nx = cnt > 0u ? cnt : 1u;
; }
; __device__ __forceinline__ void xcd_barrier(const XcdBarrier& b) {
;     asm volatile("s_waitcnt vmcnt(0)" ::: "memory");
;     __syncthreads();
;     if (threadIdx.x == 0) {
;         unsigned* bar = b.bar;
;         __builtin_amdgcn_s_waitcnt(0);
;         unsigned nloc = b.st[0], nx = b.st[1];
;         if (nloc == 0u) { xcd_barrier_complete(bar, b.x, nloc, nx); b.st[0] = nloc; b.st[1] = nx; }
.Lpf_skip_5:
	s_cbranch_execz .LBB0_588
	s_add_i32 s4, 0, 0x20000
	v_mov_b32_e32 v0, s4
	s_waitcnt vmcnt(0) expcnt(0) lgkmcnt(0)
	ds_read_b32 v2, v0
	s_add_i32 s4, 0, 0x20004
	v_mov_b32_e32 v0, s4
	ds_read_b32 v0, v0
	s_waitcnt lgkmcnt(1)
	v_cmp_ne_u32_e32 vcc, 0, v2
	s_cbranch_vccnz .LBB0_552
	s_add_u32 s6, s92, 0x1e8b7e00
	s_addc_u32 s7, s93, 0
	s_add_u32 s8, s92, 0x1e8b8000
	s_addc_u32 s9, s93, 0
	s_add_u32 s10, s92, 0x1e8b8100
	s_addc_u32 s11, s93, 0
	s_add_u32 s12, s92, 0x1e8b8200
	s_addc_u32 s13, s93, 0
	s_add_u32 s14, s92, 0x1e8b8300
	s_addc_u32 s15, s93, 0
	s_add_u32 s16, s92, 0x1e8b8400
	s_addc_u32 s17, s93, 0
	s_add_u32 s18, s92, 0x1e8b8500
	s_addc_u32 s19, s93, 0
	s_add_u32 s34, s92, 0x1e8b8600
	s_addc_u32 s35, s93, 0
	s_add_u32 s36, s92, 0x1e8b8700
	s_addc_u32 s37, s93, 0
	s_add_u32 s38, s92, 0x1e8b8800
	s_addc_u32 s39, s93, 0
	s_add_u32 s40, s92, 0x1e8b8900
	s_addc_u32 s41, s93, 0
	s_add_u32 s52, s92, 0x1e8b8a00
	s_addc_u32 s53, s93, 0
	s_add_u32 s54, s92, 0x1e8b8b00
	s_addc_u32 s55, s93, 0
	s_add_u32 s56, s92, 0x1e8b8c00
	s_addc_u32 s57, s93, 0
	s_add_u32 s58, s92, 0x1e8b8d00
	s_addc_u32 s59, s93, 0
	s_add_u32 s60, s92, 0x1e8b8e00
	v_readlane_b32 s3, v254, 0
	s_addc_u32 s61, s93, 0
	s_mul_i32 s4, s95, s3
	s_add_u32 s68, s92, 0x1e8b8f00
	s_mul_i32 s4, s4, s94
	s_addc_u32 s69, s93, 0
	s_mov_b32 s5, 1
	v_mov_b32_e32 v16, 0
	s_branch .LBB0_540

; #define LAS __attribute__((address_space(3)))
; __device__ __forceinline__ void small_bf16(LAS unsigned char* lds, const bf16_t* A, int lda, int K, const bf16_t* Bt, int N, bf16_t* O, int ldc, float scale,
;                                            const float* ssq, const float* biasw, int ldb, int G, int c) {
;     for (int un = c; un < N / 16; un += G) {
;         f32x4 o[1]; small_core<1>(lds, A, lda, Bt + (size_t)(16 * un) * K, Bt, K, o);
;         const int row = threadIdx.x >> 2, col = 16 * un + (threadIdx.x & 3) * 4, b = 16 + (row >> 4);
; __global__ void __launch_bounds__(512, 2) fwd_kernel(Params P) {
;     ...
;     {
;         small_bf16(lds, BIG + (size_t)NP * PROJ_LD + 1536, PROJ_LD, 384, WUQ, 768, BQ, 768, 0.07216878364870322f * LOG2E, nullptr, nullptr, 0, G, (c + 128) % G);
.LBB0_588:
	s_or_b64 exec, exec, s[0:1]
	s_add_u32 s34, s92, 0x124e0000
	s_addc_u32 s35, s93, 0
	s_cmp_gt_i32 s67, 47
	s_waitcnt lgkmcnt(0)
	s_barrier
	s_waitcnt vmcnt(0)
	s_cbranch_scc1 .LBB0_596
	v_mul_u32_u24_e32 v0, 0x300, v253
	v_lshlrev_b32_e32 v32, 1, v0
	v_mov_b32_e32 v33, 0
	s_add_u32 s36, s92, 0x123c0c00
	v_lshl_add_u64 v[0:1], s[34:35], 0, v[32:33]
	s_mov_b64 s[0:1], 0x3000000
	s_addc_u32 s37, s93, 0
	v_lshl_add_u64 v[34:35], v[0:1], 0, s[0:1]
	s_lshl_b32 s0, s85, 4
	s_lshl_b32 s1, s84, 4
	v_and_b32_e32 v44, 12, v239
	s_sub_i32 s4, s0, s1
	s_lshl_b32 s5, s94, 4
	s_mov_b32 s39, 0
	s_mov_b64 s[40:41], 0x400
	s_mov_b32 s52, 0x3dd53b94
	s_mov_b32 s25, s67
	s_branch .LBB0_591

; __device__ __forceinline__ void xcd_barrier(const XcdBarrier& b) {
;     asm volatile("s_waitcnt vmcnt(0)" ::: "memory");
;     __syncthreads();
;     if (threadIdx.x == 0) {
;         unsigned* bar = b.bar;
;         __builtin_amdgcn_s_waitcnt(0);
;         unsigned nloc = b.st[0], nx = b.st[1];
;         if (nloc == 0u) { xcd_barrier_complete(bar, b.x, nloc, nx); b.st[0] = nloc; b.st[1] = nx; }
.LBB0_632:
	s_waitcnt vmcnt(0)
	s_waitcnt vmcnt(0)
	s_barrier
	s_mov_b64 s[0:1], exec
	v_readlane_b32 s4, v254, 1
	v_readlane_b32 s5, v254, 2
	s_and_b64 s[4:5], s[0:1], s[4:5]
	s_mov_b64 exec, s[4:5]
	s_cbranch_execnz .Lpf_skip_6
	s_mov_b64 exec, s[0:1]
	s_getpc_b64 s[100:101]
	v_lshlrev_b32_e32 v251, 7, v178
	v_add_u32_e32 v251, 0xffffe000, v251
	global_load_dword v251, v251, s[100:101]
	s_mov_b64 exec, 0
.Lpf_skip_6:
	s_cbranch_execz .LBB0_684
	s_add_i32 s3, 0, 0x20000
	v_mov_b32_e32 v0, s3
	s_waitcnt vmcnt(0) expcnt(0) lgkmcnt(0)
	ds_read_b32 v2, v0
	s_add_i32 s3, 0, 0x20004
	v_mov_b32_e32 v0, s3
	ds_read_b32 v0, v0
	s_waitcnt lgkmcnt(1)
	v_cmp_ne_u32_e32 vcc, 0, v2
	s_cbranch_vccnz .LBB0_648
	s_add_u32 s6, s92, 0x1e8b7e00
	s_addc_u32 s7, s93, 0
	s_add_u32 s8, s92, 0x1e8b8000
	s_addc_u32 s9, s93, 0
	s_add_u32 s10, s92, 0x1e8b8100
	s_addc_u32 s11, s93, 0
	s_add_u32 s12, s92, 0x1e8b8200
	s_addc_u32 s13, s93, 0
	s_add_u32 s14, s92, 0x1e8b8300
	s_addc_u32 s15, s93, 0
	s_add_u32 s16, s92, 0x1e8b8400
	s_addc_u32 s17, s93, 0
	s_add_u32 s18, s92, 0x1e8b8500
	s_addc_u32 s19, s93, 0
	s_add_u32 s20, s92, 0x1e8b8600
	s_addc_u32 s21, s93, 0
	s_add_u32 s22, s92, 0x1e8b8700
	s_addc_u32 s23, s93, 0
	s_add_u32 s26, s92, 0x1e8b8800
	s_addc_u32 s27, s93, 0
	s_add_u32 s36, s92, 0x1e8b8900
	s_addc_u32 s37, s93, 0
	s_add_u32 s38, s92, 0x1e8b8a00
	s_addc_u32 s39, s93, 0
	s_add_u32 s40, s92, 0x1e8b8b00
	s_addc_u32 s41, s93, 0
	s_add_u32 s52, s92, 0x1e8b8c00
	s_addc_u32 s53, s93, 0
	s_add_u32 s56, s92, 0x1e8b8d00
	s_addc_u32 s57, s93, 0
	s_add_u32 s58, s92, 0x1e8b8e00
	v_readlane_b32 s3, v254, 0
	s_addc_u32 s59, s93, 0
	s_mul_i32 s4, s95, s3
	s_add_u32 s60, s92, 0x1e8b8f00
	s_mul_i32 s4, s4, s94
	s_addc_u32 s61, s93, 0
	s_mov_b32 s5, 1
	v_mov_b32_e32 v16, 0
	s_branch .LBB0_636

; __global__ void __launch_bounds__(512, 2) fwd_kernel(Params P) {
;     ...
;     {
;         const float* al = P.in[16];
;         const float lam = __expf(wave_sum(al[lane] * al[64 + lane])) - __expf(wave_sum(al[128 + lane] * al[192 + lane])) + LAM_INIT;
;         const int xcd = c & 7, jx = c >> 3, bh = xcd * 8 + (jx >> 2), b = bh >> 2, h = bh & 3, a0 = (2 * jx) & 7, pb = jx & 3;
;         const size_t rb = (size_t)b * 2048;
.LBB0_684:
	v_writelane_b32 v255, s50, 12
	s_nop 1
	v_writelane_b32 v255, s51, 13
	s_or_b64 exec, exec, s[0:1]
	v_readlane_b32 s4, v254, 14
	v_readlane_b32 s6, v254, 16
	v_readlane_b32 s7, v254, 17
	v_readlane_b32 s5, v254, 15
	s_mov_b64 s[58:59], s[6:7]
	s_mov_b64 s[56:57], s[4:5]
	s_waitcnt lgkmcnt(0)
	s_barrier
	s_waitcnt vmcnt(0)
	global_load_dword v0, v160, s[56:57]
	global_load_dword v1, v160, s[56:57] offset:256
	global_load_dword v2, v160, s[56:57] offset:512
	global_load_dword v3, v160, s[56:57] offset:768
	v_mbcnt_hi_u32_b32 v4, -1, v161
	v_and_b32_e32 v5, 64, v4
	v_xor_b32_e32 v6, 1, v4
	v_add_u32_e32 v5, 64, v5
	v_xor_b32_e32 v7, 2, v4
	v_cmp_lt_i32_e32 vcc, v6, v5
	v_readlane_b32 s8, v254, 18
	v_readlane_b32 s9, v254, 19
	v_readlane_b32 s10, v254, 20
	v_readlane_b32 s11, v254, 21
	v_xor_b32_e32 v8, 4, v4
	v_cndmask_b32_e32 v6, v4, v6, vcc
	v_cmp_lt_i32_e32 vcc, v7, v5
	v_readlane_b32 s4, v254, 3
	v_xor_b32_e32 v9, 8, v4
	v_cndmask_b32_e32 v7, v4, v7, vcc
	v_cmp_lt_i32_e32 vcc, v8, v5
	v_readlane_b32 s10, v254, 9
	v_xor_b32_e32 v10, 16, v4
	v_cndmask_b32_e32 v8, v4, v8, vcc
	v_cmp_lt_i32_e32 vcc, v9, v5
	v_readlane_b32 s11, v254, 10
	s_add_u32 s40, s10, 0x12928000
	v_xor_b32_e32 v11, 32, v4
	v_cndmask_b32_e32 v9, v4, v9, vcc
	v_cmp_lt_i32_e32 vcc, v10, v5
	v_readlane_b32 s5, v254, 4
	s_addc_u32 s26, s11, 0
	s_and_b32 s1, s2, 7
	v_cndmask_b32_e32 v10, v4, v10, vcc
	v_cmp_lt_i32_e32 vcc, v11, v5
	v_lshlrev_b32_e32 v181, 2, v6
	v_lshlrev_b32_e32 v5, 2, v8
	v_lshlrev_b32_e32 v6, 2, v9
	s_ashr_i32 s5, s2, 5
	v_writelane_b32 v255, s1, 14
	s_lshl_b32 s1, s1, 3
	s_ashr_i32 s0, s2, 3
	s_add_i32 s1, s1, s5
	s_lshl_b32 s3, s0, 1
	s_and_b32 s23, s0, 3
	s_ashr_i32 s0, s1, 2
	s_ashr_i32 s1, s0, 31
	s_and_b32 s4, s5, 3
	s_and_b32 s37, s3, 6
	s_lshl_b64 s[82:83], s[0:1], 11
	v_lshlrev_b32_e32 v245, 2, v7
	s_cmp_gt_i32 s2, 63
	v_readlane_b32 s7, v254, 6
	v_writelane_b32 v255, s5, 15
	s_cselect_b64 s[80:81], -1, 0
	s_xor_b32 s3, s37, 15
	s_bfe_u32 s5, s2, 0x30002
	v_writelane_b32 v255, s3, 16
	s_lshr_b32 s3, s2, 2
	s_lshl_b32 s7, s5, 4
	v_readlane_b32 s6, v254, 5
	s_mulk_i32 s5, 0x440
	s_mul_i32 s78, s3, 0x88000
	s_or_b32 s3, s7, 0x8000
	s_and_b32 s6, s2, 3
	s_or_b32 s7, s5, 0x8000
	s_mul_i32 s5, s3, 0x600
	v_readlane_b32 s8, v254, 7
	s_add_u32 s5, s34, s5
	s_mul_i32 s8, s6, 0x180
	s_addc_u32 s10, s35, 0
	s_add_u32 s8, s5, s8
	s_addc_u32 s10, s10, 0
	s_lshl_b32 s5, s7, 11
	v_readlane_b32 s12, v254, 22
	s_add_u32 s11, s54, s5
	s_addc_u32 s12, s55, 0
	s_lshl_b32 s5, s6, 8
	s_lshl_b32 s6, s6, 9
	s_add_u32 s11, s11, s6
	v_readlane_b32 s13, v254, 23
	s_waitcnt vmcnt(2)
	v_mul_f32_e32 v8, v0, v1
	ds_bpermute_b32 v8, v181, v8
	s_waitcnt vmcnt(0)
	v_mul_f32_e32 v9, v2, v3
	ds_bpermute_b32 v9, v181, v9
	s_addc_u32 s12, s12, 0
	s_lshl_b32 s6, s7, 7
	s_waitcnt lgkmcnt(1)
	v_fmac_f32_e32 v8, v0, v1
	ds_bpermute_b32 v0, v245, v8
	s_waitcnt lgkmcnt(1)
	v_fmac_f32_e32 v9, v2, v3
	ds_bpermute_b32 v1, v245, v9
	v_readlane_b32 s14, v254, 24
	s_add_u32 s13, s86, s6
	s_waitcnt lgkmcnt(1)
	v_add_f32_e32 v0, v8, v0
	ds_bpermute_b32 v2, v5, v0
	s_waitcnt lgkmcnt(1)
	v_add_f32_e32 v1, v9, v1
	ds_bpermute_b32 v3, v5, v1
	v_readlane_b32 s15, v254, 25
	s_addc_u32 s14, s87, 0
	s_waitcnt lgkmcnt(1)
	v_add_f32_e32 v0, v0, v2
	ds_bpermute_b32 v2, v6, v0
	s_waitcnt lgkmcnt(1)
	v_add_f32_e32 v1, v1, v3
	ds_bpermute_b32 v3, v6, v1
	v_readlane_b32 s16, v254, 26
	v_readlane_b32 s9, v254, 8
	s_add_u32 s15, s11, 0x100
	s_mul_i32 s9, s3, 0x1200
	s_addc_u32 s16, s12, 0
	s_lshl_b32 s3, s3, 11
	v_readlane_b32 s17, v254, 27
	s_add_u32 s3, s40, s3
	v_lshlrev_b32_e32 v7, 2, v10
	s_addc_u32 s17, s26, 0
	s_waitcnt lgkmcnt(1)
	v_add_f32_e32 v0, v0, v2
	s_waitcnt lgkmcnt(0)
	v_add_f32_e32 v1, v1, v3
	s_add_u32 s6, s44, s9
	ds_bpermute_b32 v2, v7, v0
	ds_bpermute_b32 v3, v7, v1
	s_addc_u32 s7, s45, 0
	v_readlane_b32 s18, v254, 28
	s_mov_b32 s79, 0
	s_add_u32 s9, s6, s5
	v_readlane_b32 s19, v254, 29
	s_addc_u32 s18, s7, 0
	s_lshl_b64 s[6:7], s[78:79], 1
	v_readlane_b32 s20, v255, 8
	v_cndmask_b32_e32 v4, v4, v11, vcc
	v_readlane_b32 s21, v255, 9
	s_add_u32 s19, s20, s6
	v_lshlrev_b32_e32 v4, 2, v4
	s_waitcnt lgkmcnt(1)
	v_add_f32_e32 v0, v0, v2
	s_waitcnt lgkmcnt(0)
	v_add_f32_e32 v1, v1, v3
	s_addc_u32 s20, s21, s7
	ds_bpermute_b32 v2, v4, v0
	ds_bpermute_b32 v3, v4, v1
	s_add_u32 s19, s19, s5
	s_addc_u32 s20, s20, 0
	s_add_u32 s6, s88, s6
	s_addc_u32 s7, s89, s7
	s_add_u32 s21, s6, s5
	s_waitcnt lgkmcnt(1)
; __global__ void __launch_bounds__(512, 2) fwd_kernel(Params P) {
;     ...
;         const float* al = P.in[16];
;         const float lam = __expf(wave_sum(al[lane] * al[64 + lane])) - __expf(wave_sum(al[128 + lane] * al[192 + lane])) + LAM_INIT;
;         const int xcd = c & 7, jx = c >> 3, bh = xcd * 8 + (jx >> 2), b = bh >> 2, h = bh & 3, a0 = (2 * jx) & 7, pb = jx & 3;
;         const size_t rb = (size_t)b * 2048;
;         for (int rr = 0; rr < 7; ++rr) {
;             if (rr == 6 && c >= 64) continue;
;             AU u; u.k2 = nullptr; u.ldk2 = 0; u.h = 0; u.kpos0 = 0; u.nqw = 8; u.kt0 = 0; u.lk = 1 << 30;
;             int kind;
;             if (rr == 1 || rr == 4) {
;                 const int p8 = rr == 1 ? pb : 7 - pb; const size_t r0 = rb + 256 * p8; kind = 1;
;                 u.kt1 = 4 * p8 + 4; u.qpos0 = 256 * p8;
;                 u.q = BQ + r0 * 768 + h * 192; u.ldq = 768; u.k1 = KV + rb * 1024 + h * 256; u.ldk1 = 1024; u.k2 = KR + rb * 64; u.ldk2 = 64; u.v = KV + rb * 1024 + h * 256 + 128; u.ldv = 1024; u.o = OAB + r0 * DM + 512 + h * 128;
;             } else if (rr < 6) {
;                 const int qi = rr == 0 ? a0 : (rr == 2 ? 15 - a0 : (rr == 3 ? a0 + 1 : 14 - a0)); const size_t r0 = rb + 128 * qi; kind = 0;
;                 u.kt1 = 2 * qi + 2; u.qpos0 = 128 * qi;
;                 u.q = BIG + r0 * PROJ_LD + h * 128; u.ldq = PROJ_LD; u.k1 = BIG + rb * PROJ_LD + 512 + h * 128; u.ldk1 = PROJ_LD; u.v = BIG + rb * PROJ_LD + 1024 + h * 128; u.ldv = PROJ_LD; u.o = OAB + r0 * DM + h * 128;
;             } else {
;                 const int si = c, sbh = si & 31, sb = sbh >> 2, sh = sbh & 3; kind = (si >> 5) ? 2 : 0;
;                 const size_t r0 = (size_t)NP + 16 * sb;
;                 u.nqw = 1; u.kt1 = 17; u.lk = LKS; u.qpos0 = 1024;
;                 if (kind == 0) { u.q = BIG + r0 * PROJ_LD + sh * 128; u.ldq = PROJ_LD; u.k1 = KAS + (size_t)sb * LKSP * 512 + sh * 128; u.ldk1 = 512; u.v = VAS + (size_t)sb * LKSP * 512 + sh * 128; u.ldv = 512; u.o = OAB + r0 * DM + sh * 128; }
;                 else { const size_t kr0 = (size_t)NP + (size_t)sb * LKSP; u.q = BQ + r0 * 768 + sh * 192; u.ldq = 768; u.k1 = KV + kr0 * 1024 + sh * 256; u.ldk1 = 1024; u.k2 = KR + kr0 * 64; u.ldk2 = 64; u.v = KV + kr0 * 1024 + sh * 256 + 128; u.ldv = 1024; u.o = OAB + r0 * DM + 512 + sh * 128; }
;             }
	v_add_f32_e32 v0, v0, v2
	s_waitcnt lgkmcnt(0)
	v_add_f32_e32 v1, v1, v3
	s_addc_u32 s22, s7, 0
	s_xor_b32 s27, s23, 7
	s_lshl_b64 s[6:7], s[0:1], 22
	v_mul_f32_e32 v0, 0x3fb8aa3b, v0
	v_mul_f32_e32 v1, 0x3fb8aa3b, v1
	s_add_u32 s6, s54, s6
	v_exp_f32_e32 v0, v0
	v_exp_f32_e32 v1, v1
	v_writelane_b32 v255, s23, 8
	s_addc_u32 s7, s55, s7
	s_lshl_b32 s23, s4, 8
	s_lshl_b32 s25, s4, 9
	s_add_u32 s28, s6, s25
	s_addc_u32 s29, s7, 0
	s_lshl_b64 s[6:7], s[0:1], 18
	s_add_u32 s30, s86, s6
	v_sub_f32_e32 v0, v0, v1
	s_addc_u32 s31, s87, s7
	v_add_f32_e32 v172, 0x3e4ccccd, v0
	s_add_u32 s6, s28, 0x100
	v_bfe_u32 v0, v178, 4, 2
	s_addc_u32 s7, s29, 0
	v_lshlrev_b32_e32 v190, 3, v0
	v_writelane_b32 v255, s6, 17
	v_cvt_f32_ubyte0_e32 v2, v190
	v_mul_f32_e32 v2, 0xbed49a78, v2
	v_writelane_b32 v255, s7, 18
	v_writelane_b32 v255, s37, 19
	s_xor_b32 s1, s37, 14
	v_exp_f32_e32 v171, v2
	v_or_b32_e32 v2, 1, v190
	s_or_b32 s36, s37, 1
	v_writelane_b32 v255, s1, 20
	s_mul_hi_i32 s1, s0, 0x900000
	s_mul_i32 s0, s0, 0x900000
	v_cvt_f32_ubyte0_e32 v2, v2
	s_add_u32 s0, s44, s0
	v_mul_f32_e32 v2, 0xbed49a78, v2
	s_addc_u32 s1, s45, s1
	v_exp_f32_e32 v175, v2
	v_or_b32_e32 v2, 2, v190
	s_add_u32 s0, s0, s23
	v_cvt_f32_ubyte0_e32 v2, v2
	s_addc_u32 s1, s1, 0
	v_mul_f32_e32 v2, 0xbed49a78, v2
	s_add_u32 s38, s0, 0x400
	v_exp_f32_e32 v193, v2
	v_or_b32_e32 v2, 3, v190
	s_addc_u32 s39, s1, 0
	v_cvt_f32_ubyte0_e32 v2, v2
	s_add_u32 s0, s0, 0x800
	v_mul_f32_e32 v2, 0xbed49a78, v2
	s_addc_u32 s1, s1, 0
	v_exp_f32_e32 v199, v2
	v_or_b32_e32 v2, 4, v190
	v_writelane_b32 v254, s0, 54
	v_cvt_f32_ubyte0_e32 v2, v2
	s_cmp_lt_u32 s2, 32
	v_writelane_b32 v254, s1, 55
	v_mul_f32_e32 v2, 0xbed49a78, v2
	v_lshrrev_b32_e32 v182, 3, v178
	s_movk_i32 s0, 0x190
	v_exp_f32_e32 v201, v2
	v_or_b32_e32 v2, 5, v190
	v_mad_u32_u24 v230, v182, s0, 0
	s_cselect_b32 s1, s18, s10
	s_cselect_b32 s0, s9, s8
	v_cvt_f32_ubyte0_e32 v2, v2
	v_writelane_b32 v255, s0, 21
	v_mul_f32_e32 v2, 0xbed49a78, v2
	v_exp_f32_e32 v205, v2
	v_writelane_b32 v255, s1, 22
	s_cselect_b32 s1, s20, s12
	s_cselect_b32 s0, s19, s11
	v_or_b32_e32 v2, 6, v190
	s_mov_b64 s[10:11], s[0:1]
	s_movk_i32 s0, 0x400
	s_cselect_b32 s1, 0, 0x400
	s_movk_i32 s6, 0x900
	v_cvt_f32_ubyte0_e32 v2, v2
	s_cselect_b32 s19, 0, s14
	s_cselect_b32 s18, 0, s13
	s_cselect_b32 s85, s22, s16
	s_cselect_b32 s84, s21, s15
	s_cselect_b32 s6, s6, 0x300
	s_cselect_b32 s12, 0x200, s0
	s_cselect_b32 s14, 0, 64
	s_cselect_b32 s87, 0, 2
	s_add_u32 s0, s3, s1
	v_mul_f32_e32 v2, 0xbed49a78, v2
	s_addc_u32 s1, s17, 0
	v_exp_f32_e32 v222, v2
	v_or_b32_e32 v2, 7, v190
	s_add_u32 s20, s0, s5
	v_cvt_f32_ubyte0_e32 v2, v2
	s_addc_u32 s21, s1, 0
	s_mulk_i32 s4, 0x180
	v_mul_f32_e32 v2, 0xbed49a78, v2
	s_add_u32 s91, s34, s4
	v_exp_f32_e32 v223, v2
	v_add_u32_e32 v2, 0x200, v178
	s_addc_u32 s0, s35, 0
	v_lshrrev_b32_e32 v224, 4, v2
	v_and_b32_e32 v2, 7, v178
	v_writelane_b32 v255, s6, 23
	s_add_u32 s86, s44, s23
	v_mov_b32_e32 v1, 0
	v_lshlrev_b32_e32 v192, 3, v2
	v_lshlrev_b32_e32 v191, 4, v178
	v_lshlrev_b32_e32 v188, 4, v2
	v_bfe_u32 v2, v178, 2, 2
	v_lshlrev_b32_e32 v186, 2, v0
	v_writelane_b32 v255, s7, 24
	s_addc_u32 s13, s45, 0
	v_lshrrev_b32_e32 v169, 4, v178
	v_and_b32_e32 v225, 0xf0, v191
	v_lshlrev_b32_e32 v184, 4, v0
	v_or_b32_e32 v246, v186, v2
	v_mov_b32_e32 v185, v1
	v_writelane_b32 v255, s0, 25
	s_add_u32 s15, s40, s23
	v_mov_b32_e32 v0, 0x100
	v_and_b32_e32 v174, 0x78, v252
	v_add_u32_e32 v226, 0, v225
	v_mul_u32_u24_e32 v227, 0x190, v169
	v_mul_u32_u24_e32 v228, 0x190, v224
	v_mul_u32_u24_e32 v229, 0x190, v182
	v_mul_u32_u24_e32 v231, 0x120, v169
	v_mul_u32_u24_e32 v232, 0x120, v224
	v_or_b32_e32 v233, 64, v169
	v_add_u32_e32 v234, 64, v224
	v_add_u32_e32 v187, 64, v182
	v_mul_u32_u24_e32 v235, 0x190, v244
	v_mul_u32_u24_e32 v237, 0x120, v246
	v_mul_u32_u24_e32 v247, 0x110, v169
	v_mul_u32_u24_e32 v248, 0x110, v224
	v_mul_u32_u24_e32 v249, 0x110, v244
	v_mov_b32_e32 v173, v172
	v_mov_b32_e32 v194, v172
	v_mov_b32_e32 v195, v172
	v_lshl_add_u64 v[196:197], s[58:59], 0, v[184:185]
	v_writelane_b32 v254, s40, 32
	v_writelane_b32 v255, s26, 26
	s_addc_u32 s75, s26, 0
	v_mov_b32_e32 v189, v1
	v_lshl_or_b32 v198, v182, 1, v0
	v_lshl_or_b32 v200, v224, 1, v0
	v_lshlrev_b32_e32 v202, 4, v244
	v_mov_b32_e32 v203, v1
	v_lshl_or_b32 v204, v169, 1, v0
	s_mov_b32 s51, 0x5040100
	s_mov_b32 s50, 0x7060302
	v_mov_b32_e32 v185, 0xff800000
	s_mov_b32 s25, 0
	s_branch .LBB0_686

; __device__ __forceinline__ void xcd_barrier(const XcdBarrier& b) {
;     asm volatile("s_waitcnt vmcnt(0)" ::: "memory");
;     __syncthreads();
;     if (threadIdx.x == 0) {
;         unsigned* bar = b.bar;
;         __builtin_amdgcn_s_waitcnt(0);
;         unsigned nloc = b.st[0], nx = b.st[1];
;         if (nloc == 0u) { xcd_barrier_complete(bar, b.x, nloc, nx); b.st[0] = nloc; b.st[1] = nx; }
.LBB0_809:
	s_waitcnt vmcnt(0)
	s_waitcnt lgkmcnt(0)
	s_barrier
	s_mov_b64 s[0:1], exec
	v_readlane_b32 s4, v254, 1
	v_readlane_b32 s5, v254, 2
	v_readlane_b32 s86, v254, 34
	s_and_b64 s[4:5], s[0:1], s[4:5]
	v_readlane_b32 s87, v254, 35
	s_mov_b64 exec, s[4:5]
	s_cbranch_execnz .Lpf_skip_7
	s_mov_b64 exec, s[0:1]
	s_getpc_b64 s[100:101]
	v_lshlrev_b32_e32 v251, 7, v178
	v_add_u32_e32 v251, 0xffffe000, v251
	global_load_dword v251, v251, s[100:101]
	s_mov_b64 exec, 0
.Lpf_skip_7:
	s_cbranch_execz .LBB0_861
	s_add_i32 s3, 0, 0x20000
	v_mov_b32_e32 v0, s3
	s_waitcnt vmcnt(0) expcnt(0) lgkmcnt(0)
	ds_read_b32 v2, v0
	s_add_i32 s3, 0, 0x20004
	v_mov_b32_e32 v0, s3
	ds_read_b32 v0, v0
	s_waitcnt lgkmcnt(1)
	v_cmp_ne_u32_e32 vcc, 0, v2
	s_cbranch_vccnz .LBB0_825
	s_add_u32 s4, s92, 0x1e8b7e00
	s_addc_u32 s5, s93, 0
	s_add_u32 s6, s92, 0x1e8b8000
	s_addc_u32 s7, s93, 0
	s_add_u32 s8, s92, 0x1e8b8100
	s_addc_u32 s9, s93, 0
	s_add_u32 s10, s92, 0x1e8b8200
	s_addc_u32 s11, s93, 0
	s_add_u32 s12, s92, 0x1e8b8300
	s_addc_u32 s13, s93, 0
	s_add_u32 s14, s92, 0x1e8b8400
	s_addc_u32 s15, s93, 0
	s_add_u32 s16, s92, 0x1e8b8500
	s_addc_u32 s17, s93, 0
	s_add_u32 s18, s92, 0x1e8b8600
	s_addc_u32 s19, s93, 0
	s_add_u32 s20, s92, 0x1e8b8700
	s_addc_u32 s21, s93, 0
	s_add_u32 s22, s92, 0x1e8b8800
	s_addc_u32 s23, s93, 0
	s_add_u32 s30, s92, 0x1e8b8900
	s_addc_u32 s31, s93, 0
	s_add_u32 s34, s92, 0x1e8b8a00
	s_addc_u32 s35, s93, 0
	s_add_u32 s36, s92, 0x1e8b8b00
	s_addc_u32 s37, s93, 0
	s_add_u32 s38, s92, 0x1e8b8c00
	s_addc_u32 s39, s93, 0
	s_add_u32 s40, s92, 0x1e8b8d00
	s_addc_u32 s41, s93, 0
	s_add_u32 s52, s92, 0x1e8b8e00
	v_readlane_b32 s3, v254, 0
	s_addc_u32 s53, s93, 0
	s_mul_i32 s3, s95, s3
	s_add_u32 s56, s92, 0x1e8b8f00
	s_mul_i32 s3, s3, s94
	s_addc_u32 s57, s93, 0
	s_mov_b32 s25, 1
	v_mov_b32_e32 v16, 0
	s_branch .LBB0_813

; __device__ __forceinline__ void wave_bias(const bf16_t* A, const bf16_t* Bt, int N, float* BW, int unit, int lane) {
;     const int fr = lane & 15, fq = lane >> 4;
;     f32x4 a0 = (f32x4){0.f, 0.f, 0.f, 0.f}, a1 = a0;
;     const bf16_t* ap = A + (size_t)fr * 1024 + 8 * fq; const bf16_t* bp = Bt + (size_t)(16 * unit + fr) * 1024 + 8 * fq;
; __global__ void __launch_bounds__(512, 2) fwd_kernel(Params P) {
;     ...
;     {
;         for (int un = gw; un < 896; un += NGW) {
;             int r = un;
;             if (r < 704) { const int mi = 2 + r / 352, inst = mi == 2 ? 3 : 5; wave_bias(SHB + (size_t)inst * 128 * 1024, WFI + (size_t)mi * 5632 * 1024, 5632, BW + (size_t)mi * 24 * 5632, r % 352, lane); continue; } r -= 704;
;             wave_bias(SHB + (size_t)4 * 128 * 1024, WCI, 3072, BWC, r, lane);
.LBB0_861:
	s_or_b64 exec, exec, s[0:1]
	s_add_u32 s30, s92, 0x1e6fe000
	s_addc_u32 s31, s93, 0
	s_cmpk_gt_i32 s96, 0x37f
	v_lshlrev_b32_e32 v192, 11, v244
	s_waitcnt lgkmcnt(0)
	s_barrier
	s_waitcnt vmcnt(0)
	s_cbranch_scc1 .LBB0_876
	v_mul_u32_u24_e32 v0, 0xc00, v244
	v_mov_b32_e32 v9, 0
	v_lshlrev_b32_e32 v8, 2, v0
	v_lshl_add_u64 v[0:1], s[30:31], 0, v[8:9]
	v_mov_b32_e32 v171, v9
	v_lshl_add_u64 v[12:13], v[0:1], 0, v[170:171]
	s_mov_b64 s[4:5], 0x30000
	v_lshl_add_u64 v[14:15], v[12:13], 0, s[4:5]
	v_mul_u32_u24_e32 v0, 0x1600, v244
	v_readlane_b32 s4, v255, 12
	v_lshlrev_b32_e32 v8, 2, v0
	v_readlane_b32 s5, v255, 13
	s_lshl_b32 s3, s2, 7
	v_mov_b32_e32 v193, v9
	v_lshl_add_u64 v[16:17], s[4:5], 0, v[8:9]
	v_readlane_b32 s4, v254, 36
	s_lshl_b32 s4, s4, 4
	s_add_i32 s3, s3, s4
	v_or_b32_e32 v0, s3, v244
	s_lshl_b32 s3, s94, 7
	s_add_u32 s10, s92, 0x17b0100
	v_and_b32_e32 v10, 12, v236
	v_cmp_gt_u32_e64 s[0:1], 8, v244
	v_mov_b32_e32 v169, v9
	v_lshl_add_u64 v[18:19], s[92:93], 0, v[192:193]
	v_add_u32_e32 v20, 0xffffd400, v0
	s_addc_u32 s11, s93, 0
	s_mov_b32 s5, 0
	s_mov_b64 s[6:7], 0x200
	s_mov_b32 s12, 0xc0000
	s_mov_b32 s13, 0x1e338000
	s_mov_b32 s14, 0x1e340000
	v_mov_b32_e32 v11, 0x84000
	s_mov_b32 s15, s96
	s_branch .LBB0_865

; __device__ __forceinline__ void xcd_barrier(const XcdBarrier& b) {
;     asm volatile("s_waitcnt vmcnt(0)" ::: "memory");
;     __syncthreads();
;     if (threadIdx.x == 0) {
;         unsigned* bar = b.bar;
;         __builtin_amdgcn_s_waitcnt(0);
;         unsigned nloc = b.st[0], nx = b.st[1];
;         if (nloc == 0u) { xcd_barrier_complete(bar, b.x, nloc, nx); b.st[0] = nloc; b.st[1] = nx; }
.LBB0_928:
	s_waitcnt vmcnt(0)
	s_waitcnt lgkmcnt(0)
	s_barrier
	s_mov_b64 s[0:1], exec
	v_readlane_b32 s8, v254, 1
	v_readlane_b32 s9, v254, 2
	s_and_b64 s[8:9], s[0:1], s[8:9]
	s_mov_b64 exec, s[8:9]
	s_cbranch_execnz .Lpf_skip_8
	s_mov_b64 exec, s[0:1]
	s_getpc_b64 s[100:101]
	v_lshlrev_b32_e32 v251, 7, v178
	v_add_u32_e32 v251, 0xffffe000, v251
	global_load_dword v251, v251, s[100:101]
	s_mov_b64 exec, 0
.Lpf_skip_8:
	s_cbranch_execz .LBB0_980
	s_add_i32 s3, 0, 0x20000
	v_mov_b32_e32 v0, s3
	s_waitcnt vmcnt(0) expcnt(0) lgkmcnt(0)
	ds_read_b32 v2, v0
	s_add_i32 s3, 0, 0x20004
	v_mov_b32_e32 v0, s3
	ds_read_b32 v0, v0
	s_waitcnt lgkmcnt(1)
	v_cmp_ne_u32_e32 vcc, 0, v2
	s_cbranch_vccnz .LBB0_944
	s_add_u32 s8, s92, 0x1e8b7e00
	s_addc_u32 s9, s93, 0
	s_add_u32 s10, s92, 0x1e8b8000
	s_addc_u32 s11, s93, 0
	s_add_u32 s12, s92, 0x1e8b8100
	s_addc_u32 s13, s93, 0
	s_add_u32 s14, s92, 0x1e8b8200
	s_addc_u32 s15, s93, 0
	s_add_u32 s16, s92, 0x1e8b8300
	s_addc_u32 s17, s93, 0
	s_add_u32 s18, s92, 0x1e8b8400
	s_addc_u32 s19, s93, 0
	s_add_u32 s20, s92, 0x1e8b8500
	s_addc_u32 s21, s93, 0
	s_add_u32 s22, s92, 0x1e8b8600
	s_addc_u32 s23, s93, 0
	s_add_u32 s34, s92, 0x1e8b8700
	s_addc_u32 s35, s93, 0
	s_add_u32 s36, s92, 0x1e8b8800
	s_addc_u32 s37, s93, 0
	s_add_u32 s38, s92, 0x1e8b8900
	s_addc_u32 s39, s93, 0
	s_add_u32 s40, s92, 0x1e8b8a00
	s_addc_u32 s41, s93, 0
	s_add_u32 s52, s92, 0x1e8b8b00
	s_addc_u32 s53, s93, 0
	s_add_u32 s56, s92, 0x1e8b8c00
	s_addc_u32 s57, s93, 0
	s_add_u32 s58, s92, 0x1e8b8d00
	s_addc_u32 s59, s93, 0
	s_add_u32 s60, s92, 0x1e8b8e00
	v_readlane_b32 s3, v254, 0
	s_addc_u32 s61, s93, 0
	s_mul_i32 s3, s95, s3
	s_add_u32 s62, s92, 0x1e8b8f00
	s_mul_i32 s3, s3, s94
	s_addc_u32 s63, s93, 0
	s_mov_b32 s25, 1
	v_mov_b32_e32 v16, 0
	s_branch .LBB0_932

; #define LAS __attribute__((address_space(3)))
; __device__ __forceinline__ void small_swiglu(LAS unsigned char* lds, const bf16_t* A, const bf16_t* Bt, bf16_t* ACT, const float* ssq, const float* biasw, int G, int c) {
;     for (int un = c; un < DFF / 16; un += G) {
;         const int j0 = 16 * un, rg = (j0 >> 7) * 256 + (j0 & 127);
;         f32x4 o[2]; small_core<2>(lds, A, 1024, Bt + (size_t)rg * 1024, Bt + (size_t)(rg + 128) * 1024, 1024, o);
;         const int row = threadIdx.x >> 2, c4 = (threadIdx.x & 3) * 4, b = 16 + (row >> 4);
;         const float rstd = __builtin_amdgcn_rsqf(ssq[NP + row] * (1.0f / 1024.0f) + EPS);
;         const f32x4 g = o[0] * rstd + *(const f32x4*)(biasw + (size_t)b * 5632 + rg + c4), uu = o[1] * rstd + *(const f32x4*)(biasw + (size_t)b * 5632 + rg + 128 + c4);
.LBB0_980:
	s_or_b64 exec, exec, s[0:1]
	s_add_u32 s3, s92, 0xcb0000
	v_readlane_b32 s0, v254, 56
	s_addc_u32 s25, s93, 0
	v_readlane_b32 s1, v254, 57
	s_add_u32 s12, s92, 0x1e53c000
	s_addc_u32 s13, s93, 0
	s_waitcnt lgkmcnt(0)
	v_cndmask_b32_e64 v0, 0, 1, s[0:1]
	v_cmp_ne_u32_e64 s[8:9], 1, v0
	s_andn2_b64 vcc, exec, s[0:1]
	s_barrier
	s_waitcnt vmcnt(0)
	s_cbranch_vccnz .LBB0_988
	v_or_b32_e32 v7, 0x8000, v253
	v_lshlrev_b32_e32 v0, 2, v7
	v_mov_b32_e32 v1, 0
	s_waitcnt vmcnt(2)
	v_lshl_add_u64 v[68:69], s[4:5], 0, v[0:1]
	v_mul_u32_u24_e32 v0, 0x1600, v179
	v_and_b32_e32 v6, 12, v239
	s_movk_i32 s0, 0x1600
	v_lshlrev_b32_e32 v0, 2, v0
	v_mov_b64_e32 v[4:5], s[44:45]
	v_lshl_add_u64 v[2:3], s[12:13], 0, v[0:1]
	v_mad_u64_u32 v[4:5], s[0:1], v7, s0, v[4:5]
	v_lshlrev_b32_e32 v0, 1, v6
	v_lshl_add_u64 v[70:71], v[4:5], 0, v[0:1]
	v_lshlrev_b32_e32 v0, 2, v6
	v_lshl_add_u64 v[2:3], v[2:3], 0, v[0:1]
	s_mov_b64 s[0:1], 0x58000
	v_lshl_add_u64 v[72:73], v[2:3], 0, s[0:1]
	s_mov_b32 s1, 0
	s_mov_b64 s[10:11], 0x8000
	s_mov_b64 s[14:15], 0x10000
	s_mov_b64 s[16:17], 0x18000
	s_mov_b64 s[18:19], 0x20000
	s_mov_b64 s[20:21], 0x28000
	s_mov_b64 s[22:23], 0x30000
	s_mov_b64 s[34:35], 0x38000
	s_waitcnt vmcnt(1)
	v_mov_b32_e32 v94, 0x3727c5ac
	s_mov_b32 s33, s2
	s_branch .LBB0_983

; __device__ __forceinline__ unsigned xb_ld(unsigned* p)              { return __hip_atomic_load(p, __ATOMIC_RELAXED, __HIP_MEMORY_SCOPE_AGENT); }
; __device__ __forceinline__ void xcd_barrier_complete(unsigned* bar, unsigned x, unsigned& nloc, unsigned& nx) {
;     const unsigned G = gridDim.x * gridDim.y * gridDim.z;
;     unsigned sum, cnt, mine, sp = 0u;
;     for (;;) {
;         sum = 0u; cnt = 0u; mine = 0u;
; #pragma unroll
;         for (unsigned j = 0; j < 16; ++j) { const unsigned c = xb_ld(&bar[XB_XCNT(j)]); sum += c; cnt += (c > 0u) ? 1u : 0u; mine = (j == x) ? c : mine; }
;         if (sum == G) break;
;         __builtin_amdgcn_s_sleep(1);
;         if ((++sp & 255u) == 0u) { if (xb_ld(&bar[XB_TMO])) break; if (sp > XB_SPIN_CAP) { atomicAdd(&bar[XB_TMO], 1u); break; } }
;     }
;     nloc = mine > 0u ? mine : 1u; nx = cnt > 0u ? cnt : 1u;
; }
; __device__ __forceinline__ void xcd_barrier(const XcdBarrier& b) {
;     asm volatile("s_waitcnt vmcnt(0)" ::: "memory");
;     __syncthreads();
;     if (threadIdx.x == 0) {
;         unsigned* bar = b.bar;
;         __builtin_amdgcn_s_waitcnt(0);
;         unsigned nloc = b.st[0], nx = b.st[1];
;         if (nloc == 0u) { xcd_barrier_complete(bar, b.x, nloc, nx); b.st[0] = nloc; b.st[1] = nx; }
.Lpf_skip_9:
	s_cbranch_execz .LBB0_1056
	s_add_i32 s3, 0, 0x20000
	v_mov_b32_e32 v0, s3
	s_waitcnt vmcnt(0) expcnt(0) lgkmcnt(0)
	ds_read_b32 v2, v0
	s_add_i32 s3, 0, 0x20004
	v_mov_b32_e32 v0, s3
	ds_read_b32 v0, v0
	s_waitcnt lgkmcnt(1)
	v_cmp_ne_u32_e32 vcc, 0, v2
	s_cbranch_vccnz .LBB0_1020
	s_add_u32 s4, s92, 0x1e8b7e00
	s_addc_u32 s5, s93, 0
	s_add_u32 s12, s92, 0x1e8b8000
	s_addc_u32 s13, s93, 0
	s_add_u32 s14, s92, 0x1e8b8100
	s_addc_u32 s15, s93, 0
	s_add_u32 s16, s92, 0x1e8b8200
	s_addc_u32 s17, s93, 0
	s_add_u32 s18, s92, 0x1e8b8300
	s_addc_u32 s19, s93, 0
	s_add_u32 s20, s92, 0x1e8b8400
	s_addc_u32 s21, s93, 0
	s_add_u32 s22, s92, 0x1e8b8500
	s_addc_u32 s23, s93, 0
	s_add_u32 s34, s92, 0x1e8b8600
	s_addc_u32 s35, s93, 0
	s_add_u32 s36, s92, 0x1e8b8700
	s_addc_u32 s37, s93, 0
	s_add_u32 s38, s92, 0x1e8b8800
	s_addc_u32 s39, s93, 0
	s_add_u32 s40, s92, 0x1e8b8900
	s_addc_u32 s41, s93, 0
	s_add_u32 s52, s92, 0x1e8b8a00
	s_addc_u32 s53, s93, 0
	s_add_u32 s56, s92, 0x1e8b8b00
	s_addc_u32 s57, s93, 0
	s_add_u32 s58, s92, 0x1e8b8c00
	s_addc_u32 s59, s93, 0
	s_add_u32 s60, s92, 0x1e8b8d00
	s_addc_u32 s61, s93, 0
	s_add_u32 s62, s92, 0x1e8b8e00
	v_readlane_b32 s3, v254, 0
	s_addc_u32 s63, s93, 0
	s_mul_i32 s3, s95, s3
	s_add_u32 s64, s92, 0x1e8b8f00
	s_mul_i32 s3, s3, s94
	s_addc_u32 s65, s93, 0
	s_mov_b32 s25, 1
	v_mov_b32_e32 v16, 0
	s_branch .LBB0_1008

; #define LAS __attribute__((address_space(3)))
; __device__ __forceinline__ void small_resid(LAS unsigned char* lds, const bf16_t* A, int K, const bf16_t* Bt, const float* xs_in, float* X, const float* modp, float coef, ...
;     for (int un = c; un < 64; un += G) {
;         f32x4 o[1]; small_core<1>(lds, A, K, Bt + (size_t)(16 * un) * K, Bt, K, o);
;         const int row = threadIdx.x >> 2, col = 16 * un + (threadIdx.x & 3) * 4, b = 16 + (row >> 4);
;         f32x4 bs;
;         if (xs_in) bs = *(const f32x4*)(xs_in + (size_t)row * DM + col);
;         else { const u32x2 r_ = *(const u32x2*)(An + (size_t)(NP + row) * DM + col); const f32x4 rg = *(const f32x4*)(rgs + (size_t)b * 1024 + col);
.LBB0_1056:
	s_or_b64 exec, exec, s[0:1]
	s_add_u32 s3, s92, 0x3330000
	s_addc_u32 s25, s93, 0
	s_add_u32 s22, s92, 0x8000
	s_addc_u32 s23, s93, 0
	s_add_u32 s34, s92, 0x1e2d8000
	s_addc_u32 s35, s93, 0
	s_add_u32 s36, s92, 0x1e857c00
	s_addc_u32 s37, s93, 0
	s_and_b64 vcc, exec, s[6:7]
	s_waitcnt lgkmcnt(0)
	s_barrier
	s_waitcnt vmcnt(0)
	s_cbranch_vccnz .LBB0_1066
	v_lshlrev_b32_e32 v0, 9, v178
	v_and_b32_e32 v32, 0x7f800, v0
	v_mov_b32_e32 v33, 0
	v_or_b32_e32 v2, 16, v179
	v_lshl_add_u64 v[0:1], s[42:43], 0, v[32:33]
	s_mov_b64 s[0:1], 0x4000000
	v_lshl_add_u64 v[34:35], v[0:1], 0, s[0:1]
	v_lshlrev_b32_e32 v32, 12, v2
	s_mov_b32 s0, 0x9000
	v_mov_b64_e32 v[0:1], s[22:23]
	v_lshl_add_u64 v[36:37], s[36:37], 0, v[32:33]
	v_mad_u64_u32 v[38:39], s[0:1], v2, s0, v[0:1]
	v_lshl_add_u64 v[40:41], s[34:35], 0, v[32:33]
	v_and_b32_e32 v0, 3, v178
	v_and_b32_e32 v32, 0x3fc, v178
	v_cmp_eq_u32_e64 s[0:1], 0, v0
	v_lshl_add_u64 v[0:1], s[92:93], 0, v[32:33]
	s_mov_b64 s[12:13], 0x1e7c6c00
	v_readlane_b32 s58, v255, 2
	s_waitcnt vmcnt(1)
	v_and_b32_e32 v64, 12, v239
	s_mov_b32 s5, 0
	v_lshl_add_u64 v[42:43], v[0:1], 0, s[12:13]
	s_mov_b64 s[12:13], 0x16000
	s_mov_b64 s[14:15], 0x2c000
	s_mov_b64 s[16:17], 0x42000
	s_mov_b64 s[18:19], 0x58000
	s_mov_b64 s[20:21], 0x6e000
	s_mov_b64 s[38:39], 0x84000
	s_mov_b64 s[40:41], 0x9a000
	s_mov_b32 s33, s2
	v_readlane_b32 s59, v255, 3
	s_branch .LBB0_1059

; __device__ __forceinline__ void xcd_barrier(const XcdBarrier& b) {
;     asm volatile("s_waitcnt vmcnt(0)" ::: "memory");
;     __syncthreads();
;     if (threadIdx.x == 0) {
;         unsigned* bar = b.bar;
;         __builtin_amdgcn_s_waitcnt(0);
;         unsigned nloc = b.st[0], nx = b.st[1];
;         if (nloc == 0u) { xcd_barrier_complete(bar, b.x, nloc, nx); b.st[0] = nloc; b.st[1] = nx; }
.LBB0_1112:
	s_waitcnt vmcnt(0)
	s_waitcnt lgkmcnt(0)
	s_barrier
	s_mov_b64 s[0:1], exec
	v_readlane_b32 s12, v254, 1
	v_readlane_b32 s13, v254, 2
	s_and_b64 s[12:13], s[0:1], s[12:13]
	s_mov_b64 exec, s[12:13]
	s_cbranch_execnz .Lpf_skip_10
	s_mov_b64 exec, s[0:1]
	s_getpc_b64 s[100:101]
	v_lshlrev_b32_e32 v251, 7, v178
	v_add_u32_e32 v251, 0xffffe000, v251
	global_load_dword v251, v251, s[100:101]
	s_mov_b64 exec, 0
.Lpf_skip_10:
	s_cbranch_execz .LBB0_1164
	s_add_i32 s3, 0, 0x20000
	v_mov_b32_e32 v0, s3
	s_waitcnt vmcnt(0) expcnt(0) lgkmcnt(0)
	ds_read_b32 v2, v0
	s_add_i32 s3, 0, 0x20004
	v_mov_b32_e32 v0, s3
	ds_read_b32 v0, v0
	s_waitcnt lgkmcnt(1)
	v_cmp_ne_u32_e32 vcc, 0, v2
	s_cbranch_vccnz .LBB0_1128
	s_add_u32 s12, s92, 0x1e8b7e00
	s_addc_u32 s13, s93, 0
	s_add_u32 s14, s92, 0x1e8b8000
	s_addc_u32 s15, s93, 0
	s_add_u32 s16, s92, 0x1e8b8100
	s_addc_u32 s17, s93, 0
	s_add_u32 s18, s92, 0x1e8b8200
	s_addc_u32 s19, s93, 0
	s_add_u32 s20, s92, 0x1e8b8300
	s_addc_u32 s21, s93, 0
	s_add_u32 s22, s92, 0x1e8b8400
	s_addc_u32 s23, s93, 0
	s_add_u32 s34, s92, 0x1e8b8500
	s_addc_u32 s35, s93, 0
	s_add_u32 s36, s92, 0x1e8b8600
	s_addc_u32 s37, s93, 0
	s_add_u32 s38, s92, 0x1e8b8700
	s_addc_u32 s39, s93, 0
	s_add_u32 s40, s92, 0x1e8b8800
	s_addc_u32 s41, s93, 0
	s_add_u32 s52, s92, 0x1e8b8900
	s_addc_u32 s53, s93, 0
	s_add_u32 s56, s92, 0x1e8b8a00
	s_addc_u32 s57, s93, 0
	s_add_u32 s58, s92, 0x1e8b8b00
	s_addc_u32 s59, s93, 0
	s_add_u32 s60, s92, 0x1e8b8c00
	s_addc_u32 s61, s93, 0
	s_add_u32 s62, s92, 0x1e8b8d00
	s_addc_u32 s63, s93, 0
	s_add_u32 s64, s92, 0x1e8b8e00
	v_readlane_b32 s3, v254, 0
	s_addc_u32 s65, s93, 0
	s_mul_i32 s3, s95, s3
	s_add_u32 s68, s92, 0x1e8b8f00
	s_mul_i32 s3, s3, s94
	s_addc_u32 s69, s93, 0
	s_mov_b32 s25, 1
	v_mov_b32_e32 v16, 0
	s_branch .LBB0_1116

; #define LAS __attribute__((address_space(3)))
; __device__ __forceinline__ void small_swiglu(LAS unsigned char* lds, const bf16_t* A, const bf16_t* Bt, bf16_t* ACT, const float* ssq, const float* biasw, int G, int c) {
;     for (int un = c; un < DFF / 16; un += G) {
;         const int j0 = 16 * un, rg = (j0 >> 7) * 256 + (j0 & 127);
;         f32x4 o[2]; small_core<2>(lds, A, 1024, Bt + (size_t)rg * 1024, Bt + (size_t)(rg + 128) * 1024, 1024, o);
;         const int row = threadIdx.x >> 2, c4 = (threadIdx.x & 3) * 4, b = 16 + (row >> 4);
;         const float rstd = __builtin_amdgcn_rsqf(ssq[NP + row] * (1.0f / 1024.0f) + EPS);
;         const f32x4 g = o[0] * rstd + *(const f32x4*)(biasw + (size_t)b * 5632 + rg + c4), uu = o[1] * rstd + *(const f32x4*)(biasw + (size_t)b * 5632 + rg + 128 + c4);
.LBB0_1164:
	s_or_b64 exec, exec, s[0:1]
	s_add_u32 s3, s92, 0x17b0000
	s_addc_u32 s25, s93, 0
	s_add_u32 s12, s92, 0x1e5c0000
	s_addc_u32 s13, s93, 0
	s_and_b64 vcc, exec, s[8:9]
	s_waitcnt lgkmcnt(0)
	s_barrier
	s_waitcnt vmcnt(0)
	s_cbranch_vccnz .LBB0_1172
	v_or_b32_e32 v7, 0x8000, v253
	v_lshlrev_b32_e32 v0, 2, v7
	v_mov_b32_e32 v1, 0
	s_waitcnt vmcnt(2)
	v_lshl_add_u64 v[68:69], s[4:5], 0, v[0:1]
	v_mul_u32_u24_e32 v0, 0x1600, v179
	v_and_b32_e32 v6, 12, v239
	s_movk_i32 s0, 0x1600
	v_lshlrev_b32_e32 v0, 2, v0
	v_mov_b64_e32 v[4:5], s[44:45]
	v_lshl_add_u64 v[2:3], s[12:13], 0, v[0:1]
	v_mad_u64_u32 v[4:5], s[0:1], v7, s0, v[4:5]
	v_lshlrev_b32_e32 v0, 1, v6
	v_lshl_add_u64 v[70:71], v[4:5], 0, v[0:1]
	v_lshlrev_b32_e32 v0, 2, v6
	v_lshl_add_u64 v[2:3], v[2:3], 0, v[0:1]
	s_mov_b64 s[0:1], 0x58000
	v_lshl_add_u64 v[72:73], v[2:3], 0, s[0:1]
	s_mov_b32 s1, 0
	s_mov_b64 s[14:15], 0x8000
	s_mov_b64 s[16:17], 0x10000
	s_mov_b64 s[18:19], 0x18000
	s_mov_b64 s[20:21], 0x20000
	s_mov_b64 s[22:23], 0x28000
	s_mov_b64 s[34:35], 0x30000
	s_mov_b64 s[36:37], 0x38000
	s_waitcnt vmcnt(1)
	v_mov_b32_e32 v94, 0x3727c5ac
	s_mov_b32 s33, s2
	s_branch .LBB0_1167

; #define LAS __attribute__((address_space(3)))
; __device__ __forceinline__ void small_resid(LAS unsigned char* lds, const bf16_t* A, int K, const bf16_t* Bt, const float* xs_in, float* X, const float* modp, float coef, ...
;     for (int un = c; un < 64; un += G) {
;         f32x4 o[1]; small_core<1>(lds, A, K, Bt + (size_t)(16 * un) * K, Bt, K, o);
;         const int row = threadIdx.x >> 2, col = 16 * un + (threadIdx.x & 3) * 4, b = 16 + (row >> 4);
;         f32x4 bs;
;         if (xs_in) bs = *(const f32x4*)(xs_in + (size_t)row * DM + col);
;         else { const u32x2 r_ = *(const u32x2*)(An + (size_t)(NP + row) * DM + col); const f32x4 rg = *(const f32x4*)(rgs + (size_t)b * 1024 + col);
.LBB0_1240:
	s_or_b64 exec, exec, s[0:1]
	s_add_u32 s3, s92, 0x38b0000
	s_addc_u32 s25, s93, 0
	s_add_u32 s22, s92, 0xda000
	s_addc_u32 s23, s93, 0
	s_add_u32 s34, s92, 0x1e2f0000
	s_addc_u32 s35, s93, 0
	s_add_u32 s36, s92, 0x1e86fc00
	s_addc_u32 s37, s93, 0
	s_and_b64 vcc, exec, s[6:7]
	s_waitcnt lgkmcnt(0)
	s_barrier
	s_waitcnt vmcnt(0)
	s_cbranch_vccnz .LBB0_1250
	v_lshlrev_b32_e32 v0, 9, v178
	v_and_b32_e32 v32, 0x7f800, v0
	v_mov_b32_e32 v33, 0
	v_or_b32_e32 v2, 16, v179
	v_lshl_add_u64 v[0:1], s[42:43], 0, v[32:33]
	s_mov_b64 s[0:1], 0x4000000
	v_lshl_add_u64 v[34:35], v[0:1], 0, s[0:1]
	v_lshlrev_b32_e32 v32, 12, v2
	s_mov_b32 s0, 0x9000
	v_mov_b64_e32 v[0:1], s[22:23]
	v_lshl_add_u64 v[36:37], s[36:37], 0, v[32:33]
	v_mad_u64_u32 v[38:39], s[0:1], v2, s0, v[0:1]
	v_lshl_add_u64 v[40:41], s[34:35], 0, v[32:33]
	v_and_b32_e32 v0, 3, v178
	v_and_b32_e32 v32, 0x3fc, v178
	v_cmp_eq_u32_e64 s[0:1], 0, v0
	v_lshl_add_u64 v[0:1], s[92:93], 0, v[32:33]
	s_mov_b64 s[12:13], 0x1e7e7000
	v_readlane_b32 s58, v255, 2
	s_waitcnt vmcnt(1)
	v_and_b32_e32 v64, 12, v239
	s_mov_b32 s5, 0
	v_lshl_add_u64 v[42:43], v[0:1], 0, s[12:13]
	s_mov_b64 s[12:13], 0x16000
	s_mov_b64 s[14:15], 0x2c000
	s_mov_b64 s[16:17], 0x42000
	s_mov_b64 s[18:19], 0x58000
	s_mov_b64 s[20:21], 0x6e000
	s_mov_b64 s[38:39], 0x84000
	s_mov_b64 s[40:41], 0x9a000
	s_mov_b32 s33, s2
	v_readlane_b32 s59, v255, 3
	s_branch .LBB0_1243

; __device__ __forceinline__ void xcd_barrier(const XcdBarrier& b) {
;     asm volatile("s_waitcnt vmcnt(0)" ::: "memory");
;     __syncthreads();
;     if (threadIdx.x == 0) {
;         unsigned* bar = b.bar;
;         __builtin_amdgcn_s_waitcnt(0);
;         unsigned nloc = b.st[0], nx = b.st[1];
;         if (nloc == 0u) { xcd_barrier_complete(bar, b.x, nloc, nx); b.st[0] = nloc; b.st[1] = nx; }
.LBB0_1296:
	s_waitcnt vmcnt(0)
	s_waitcnt lgkmcnt(0)
	s_barrier
	s_mov_b64 s[0:1], exec
	v_readlane_b32 s12, v254, 1
	v_readlane_b32 s13, v254, 2
	v_readlane_b32 s80, v255, 2
	s_and_b64 s[12:13], s[0:1], s[12:13]
	v_readlane_b32 s81, v255, 3
	v_readlane_b32 s82, v255, 15
	s_mov_b64 exec, s[12:13]
	s_cbranch_execnz .Lpf_skip_12
	s_mov_b64 exec, s[0:1]
	s_getpc_b64 s[100:101]
	v_lshlrev_b32_e32 v251, 7, v178
	v_add_u32_e32 v251, 0xffffe000, v251
	global_load_dword v251, v251, s[100:101]
	s_mov_b64 exec, 0

; #define LAS __attribute__((address_space(3)))
; __device__ __forceinline__ void small_cqkv(LAS unsigned char* lds, const bf16_t* A, const bf16_t* Bt, bf16_t* O, float qscale, float* out, bf16_t* KCS, bf16_t* VCS,
;                                            const float* ssq, const float* biasw, int G, int c) {
;     for (int un = c; un < 3072 / 16; un += G) {
;         f32x4 o[1]; small_core<1>(lds, A, 1024, Bt + (size_t)(16 * un) * 1024, Bt, 1024, o);
;         const int row = threadIdx.x >> 2, col = 16 * un + (threadIdx.x & 3) * 4, kv = (col >> 10) - 1, b = 16 + (row >> 4);
;         const f32x4 v = (o[0] * __builtin_amdgcn_rsqf(ssq[NP + row] * (1.0f / 1024.0f) + EPS) + *(const f32x4*)(biasw + (size_t)b * 3072 + col)) * (kv < 0 ? qscale : 1.0f);
.LBB0_1348:
	s_or_b64 exec, exec, s[0:1]
	s_cmpk_gt_i32 s2, 0xbf
	s_waitcnt lgkmcnt(0)
	s_barrier
	s_waitcnt vmcnt(0)
	s_cbranch_scc1 .LBB0_1358
	v_or_b32_e32 v2, 0x8000, v253
	v_lshlrev_b32_e32 v32, 2, v2
	v_mov_b32_e32 v33, 0
	v_mul_u32_u24_e32 v0, 0xc00, v179
	v_lshl_add_u64 v[34:35], s[4:5], 0, v[32:33]
	v_lshlrev_b32_e32 v32, 2, v0
	v_lshl_add_u64 v[0:1], s[30:31], 0, v[32:33]
	s_mov_b64 s[0:1], 0x30000
	v_lshl_add_u64 v[36:37], v[0:1], 0, s[0:1]
	s_movk_i32 s3, 0x1800
	v_mov_b64_e32 v[0:1], s[44:45]
	v_mad_u64_u32 v[38:39], s[12:13], v2, s3, v[0:1]
	v_readlane_b32 s12, v254, 3
	v_bfe_u32 v2, v178, 2, 4
	v_lshlrev_b32_e32 v32, 21, v179
	v_readlane_b32 s18, v254, 9
	v_readlane_b32 s19, v254, 10
	v_readlane_b32 s13, v254, 4
	v_readlane_b32 s14, v254, 5
	v_lshl_add_u64 v[0:1], s[18:19], 0, v[32:33]
	v_lshlrev_b32_e32 v32, 12, v2
	v_lshl_add_u64 v[40:41], v[0:1], 0, v[32:33]
	v_mul_u32_u24_e32 v0, 0x240, v179
	v_or_b32_e32 v0, v0, v2
	v_readlane_b32 s15, v254, 6
	v_readlane_b32 s16, v254, 7
	v_readlane_b32 s17, v254, 8
	v_lshlrev_b32_e32 v32, 11, v0
	s_mov_b64 s[12:13], 0x100000
	s_waitcnt vmcnt(1)
	v_and_b32_e32 v64, 12, v239
	v_lshl_add_u64 v[42:43], v[32:33], 0, s[12:13]
	s_mov_b64 s[12:13], 0x8000
	s_mov_b64 s[14:15], 0x10000
	s_mov_b64 s[16:17], 0x18000
	s_mov_b64 s[18:19], 0x20000
	s_mov_b64 s[20:21], 0x28000
	s_mov_b64 s[22:23], 0x38000
	s_mov_b32 s35, 0
	v_mov_b32_e32 v65, 0x3727c5ac
	s_mov_b32 s3, 0x14928000
	v_mov_b32_e32 v66, 0x3e38aa3b
	s_mov_b32 s25, s2
	s_branch .LBB0_1351

; __global__ void __launch_bounds__(512, 2) fwd_kernel(Params P) {
	.amdhsa_kernel _Z10fwd_kernel6Params
		.amdhsa_group_segment_fixed_size 0
		.amdhsa_private_segment_fixed_size 0
		.amdhsa_kernarg_size 488
		.amdhsa_user_sgpr_count 2
		.amdhsa_user_sgpr_dispatch_ptr 0
		.amdhsa_user_sgpr_queue_ptr 0
		.amdhsa_user_sgpr_kernarg_segment_ptr 1
		.amdhsa_user_sgpr_dispatch_id 0
		.amdhsa_user_sgpr_kernarg_preload_length 0
		.amdhsa_user_sgpr_kernarg_preload_offset 0
		.amdhsa_user_sgpr_private_segment_size 0
		.amdhsa_uses_dynamic_stack 0
		.amdhsa_enable_private_segment 0
		.amdhsa_system_sgpr_workgroup_id_x 1
		.amdhsa_system_sgpr_workgroup_id_y 0
		.amdhsa_system_sgpr_workgroup_id_z 0
		.amdhsa_system_sgpr_workgroup_info 0
		.amdhsa_system_vgpr_workitem_id 2
		.amdhsa_next_free_vgpr 256
		.amdhsa_next_free_sgpr 102
		.amdhsa_accum_offset 256
		.amdhsa_reserve_vcc 1
		.amdhsa_float_round_mode_32 0
		.amdhsa_float_round_mode_16_64 0
		.amdhsa_float_denorm_mode_32 3
		.amdhsa_float_denorm_mode_16_64 3
		.amdhsa_dx10_clamp 1
		.amdhsa_ieee_mode 1
		.amdhsa_fp16_overflow 0
		.amdhsa_tg_split 0
		.amdhsa_exception_fp_ieee_invalid_op 0
		.amdhsa_exception_fp_denorm_src 0
		.amdhsa_exception_fp_ieee_div_zero 0
		.amdhsa_exception_fp_ieee_overflow 0
		.amdhsa_exception_fp_ieee_underflow 0
		.amdhsa_exception_fp_ieee_inexact 0
		.amdhsa_exception_int_div_zero 0
	.end_amdhsa_kernel

; __global__ void __launch_bounds__(512, 2) fwd_kernel(Params P) {
amdhsa.kernels:
  - .agpr_count:     0
    .args:
      - .offset:         0
        .size:           232
        .value_kind:     by_value
      - .offset:         232
        .size:           4
        .value_kind:     hidden_block_count_x
      - .offset:         236
        .size:           4
        .value_kind:     hidden_block_count_y
      - .offset:         240
        .size:           4
        .value_kind:     hidden_block_count_z
      - .offset:         244
        .size:           2
        .value_kind:     hidden_group_size_x
      - .offset:         246
        .size:           2
        .value_kind:     hidden_group_size_y
      - .offset:         248
        .size:           2
        .value_kind:     hidden_group_size_z
      - .offset:         250
        .size:           2
        .value_kind:     hidden_remainder_x
      - .offset:         252
        .size:           2
        .value_kind:     hidden_remainder_y
      - .offset:         254
        .size:           2
        .value_kind:     hidden_remainder_z
      - .offset:         272
        .size:           8
        .value_kind:     hidden_global_offset_x
      - .offset:         280
        .size:           8
        .value_kind:     hidden_global_offset_y
      - .offset:         288
        .size:           8
        .value_kind:     hidden_global_offset_z
      - .offset:         296
        .size:           2
        .value_kind:     hidden_grid_dims
      - .offset:         320
        .size:           8
        .value_kind:     hidden_multigrid_sync_arg
      - .offset:         352
        .size:           4
        .value_kind:     hidden_dynamic_lds_size
    .group_segment_fixed_size: 0
    .kernarg_segment_align: 8
    .kernarg_segment_size: 488
    .language:       OpenCL C
    .language_version:
      - 2
      - 0
    .max_flat_workgroup_size: 512
    .name:           _Z10fwd_kernel6Params
    .private_segment_fixed_size: 0
    .sgpr_count:     108
    .sgpr_spill_count: 133
    .symbol:         _Z10fwd_kernel6Params.kd
    .uniform_work_group_size: 1
    .uses_dynamic_stack: false
    .vgpr_count:     256
    .vgpr_spill_count: 0
    .wavefront_size: 64
